# v071 with +256B row padding (8448B / 4352B strides) instead of +128B
# baseline (speedup 1.0000x reference)
; __device__ __forceinline__ unsigned cvt_pk_bf16(float lo, float hi) { unsigned r; asm volatile("v_cvt_pk_bf16_f32 %0, %1, %2" : "=v"(r) : "v"(lo), "v"(hi)); return r; }
; __device__ __forceinline__ float fast_sigmoid(float x) { return __builtin_amdgcn_rcpf(1.0f + __builtin_amdgcn_exp2f(-x * LOG2E)); }
;     __device__ __forceinline__ void operator()(EPI_ARGS) const {
;     ...
; #pragma unroll
;             for (int ai = 0; ai < 2; ++ai)
; #pragma unroll
;                 for (int m = 0; m < 4; ++m) {
;                     const float rs = I8 ? rtab[wr * 64 + fr + ai * HALF + m * 16] : 1.0f;
;                     f32x4 o[2];
; #pragma unroll
;                     for (int n = 0; n < 2; ++n) { f32x4 a = acc[ai][0][m][n], b = acc[ai][1][m][n];
;                         if (I8) { const i32x4 ia = __builtin_bit_cast(i32x4, a), ib = __builtin_bit_cast(i32x4, b);
;                             a = (f32x4){(float)ia[0], (float)ia[1], (float)ia[2], (float)ia[3]} * (sb[0][n] * rs); b = (f32x4){(float)ib[0], (float)ib[1], (float)ib[2], (float)ib[3]} * (sb[1][n] * rs); }
; #pragma unroll
;                         for (int e = 0; e < 4; ++e) o[n][e] = glu ? a[e] * fast_sigmoid(b[e]) : a[e] * b[e]; }
;                     u32x4 w; w.x = cvt_pk_bf16(o[0][0], o[0][1]); w.y = cvt_pk_bf16(o[0][2], o[0][3]); w.z = cvt_pk_bf16(o[1][0], o[1][1]); w.w = cvt_pk_bf16(o[1][2], o[1][3]);
;                     *(u32x4*)(base + (size_t)(row0 + ai * HALF + m * 16) * CWID) = w; }
;         } else {
;             bf16* base = BG + (size_t)((pn - 32) * BM + c8);
; #pragma unroll
;             for (int ai = 0; ai < 2; ++ai)
; #pragma unroll
;                 for (int m = 0; m < 4; ++m)
; #pragma unroll
;                     for (int bj = 0; bj < 2; ++bj) { const f32x4 v0 = acc[ai][bj][m][0], v1 = acc[ai][bj][m][1];
;                         u32x4 w; w.x = cvt_pk_bf16(v0[0], v0[1]); w.y = cvt_pk_bf16(v0[2], v0[3]); w.z = cvt_pk_bf16(v1[0], v1[1]); w.w = cvt_pk_bf16(v1[2], v1[3]);
;                         *(u32x4*)(base + (size_t)(row0 + ai * HALF + m * 16) * CWID + bj * HALF) = w; }
.LBB0_564:
	s_nop 7
	v_lshl_add_u32 v245, s0, 8, v151
	v_mul_u32_u24_e32 v245, 0x1100, v245
	v_bfe_u32 v246, v0, 6, 2
	v_bfe_u32 v255, v0, 4, 2
	v_lshlrev_b32_e32 v246, 6, v246
	v_lshl_add_u32 v246, v255, 4, v246
	v_add_u32_e32 v245, v245, v246
	s_cmp_gt_i32 s91, 15
	s_cbranch_scc1 .Lmy_p1b_bg
	s_lshl_b32 s0, s91, 8
	v_add_u32_e32 v245, s0, v245
	v_readlane_b32 s0, v244, 47
	v_readlane_b32 s1, v244, 48
	s_nop 4
	v_pk_mul_f32 v[126:127], v[126:127], v[122:123]
	v_pk_mul_f32 v[128:129], v[128:129], v[124:125]
	v_cvt_pk_bf16_f32 v136, v126, v127
	v_cvt_pk_bf16_f32 v137, v128, v129
	v_pk_mul_f32 v[118:119], v[118:119], v[114:115]
	v_pk_mul_f32 v[120:121], v[120:121], v[116:117]
	v_cvt_pk_bf16_f32 v138, v118, v119
	v_cvt_pk_bf16_f32 v139, v120, v121
	global_store_dwordx4 v245, v[136:139], s[0:1]
	v_pk_mul_f32 v[110:111], v[110:111], v[106:107]
	v_pk_mul_f32 v[112:113], v[112:113], v[108:109]
	v_cvt_pk_bf16_f32 v140, v110, v111
	v_cvt_pk_bf16_f32 v141, v112, v113
	v_pk_mul_f32 v[102:103], v[102:103], v[98:99]
	v_pk_mul_f32 v[104:105], v[104:105], v[100:101]
	v_cvt_pk_bf16_f32 v142, v102, v103
	v_cvt_pk_bf16_f32 v143, v104, v105
	v_add_u32_e32 v246, 0x11000, v245
	global_store_dwordx4 v246, v[140:143], s[0:1]
	v_pk_mul_f32 v[94:95], v[94:95], v[90:91]
	v_pk_mul_f32 v[96:97], v[96:97], v[92:93]
	v_cvt_pk_bf16_f32 v158, v94, v95
	v_cvt_pk_bf16_f32 v159, v96, v97
	v_pk_mul_f32 v[86:87], v[86:87], v[82:83]
	v_pk_mul_f32 v[88:89], v[88:89], v[84:85]
	v_cvt_pk_bf16_f32 v160, v86, v87
	v_cvt_pk_bf16_f32 v161, v88, v89
	v_add_u32_e32 v255, 0x22000, v245
	global_store_dwordx4 v255, v[158:161], s[0:1]
	v_pk_mul_f32 v[78:79], v[78:79], v[74:75]
	v_pk_mul_f32 v[80:81], v[80:81], v[76:77]
	v_cvt_pk_bf16_f32 v162, v78, v79
	v_cvt_pk_bf16_f32 v163, v80, v81
	v_pk_mul_f32 v[70:71], v[70:71], v[66:67]
	v_pk_mul_f32 v[72:73], v[72:73], v[68:69]
	v_cvt_pk_bf16_f32 v164, v70, v71
	v_cvt_pk_bf16_f32 v165, v72, v73
	v_add_u32_e32 v246, 0x33000, v245
	global_store_dwordx4 v246, v[162:165], s[0:1]
	v_pk_mul_f32 v[62:63], v[62:63], v[58:59]
	v_pk_mul_f32 v[64:65], v[64:65], v[60:61]
	v_cvt_pk_bf16_f32 v166, v62, v63
	v_cvt_pk_bf16_f32 v167, v64, v65
	v_pk_mul_f32 v[54:55], v[54:55], v[50:51]
	v_pk_mul_f32 v[56:57], v[56:57], v[52:53]
	v_cvt_pk_bf16_f32 v168, v54, v55
	v_cvt_pk_bf16_f32 v169, v56, v57
	v_add_u32_e32 v255, 0x88000, v245
	global_store_dwordx4 v255, v[166:169], s[0:1]
	v_pk_mul_f32 v[46:47], v[46:47], v[42:43]
	v_pk_mul_f32 v[48:49], v[48:49], v[44:45]
	v_cvt_pk_bf16_f32 v170, v46, v47
	v_cvt_pk_bf16_f32 v171, v48, v49
	v_pk_mul_f32 v[38:39], v[38:39], v[34:35]
	v_pk_mul_f32 v[40:41], v[40:41], v[36:37]
	v_cvt_pk_bf16_f32 v172, v38, v39
	v_cvt_pk_bf16_f32 v173, v40, v41
	v_add_u32_e32 v246, 0x99000, v245
	global_store_dwordx4 v246, v[170:173], s[0:1]
	v_pk_mul_f32 v[30:31], v[30:31], v[26:27]
	v_pk_mul_f32 v[32:33], v[32:33], v[28:29]
	v_cvt_pk_bf16_f32 v174, v30, v31
	v_cvt_pk_bf16_f32 v175, v32, v33
	v_pk_mul_f32 v[22:23], v[22:23], v[18:19]
	v_pk_mul_f32 v[24:25], v[24:25], v[20:21]
	v_cvt_pk_bf16_f32 v176, v22, v23
	v_cvt_pk_bf16_f32 v177, v24, v25
	v_add_u32_e32 v255, 0xaa000, v245
	global_store_dwordx4 v255, v[174:177], s[0:1]
	v_pk_mul_f32 v[14:15], v[14:15], v[10:11]
	v_pk_mul_f32 v[16:17], v[16:17], v[12:13]
	v_cvt_pk_bf16_f32 v178, v14, v15
	v_cvt_pk_bf16_f32 v179, v16, v17
	v_pk_mul_f32 v[6:7], v[6:7], v[2:3]
	v_pk_mul_f32 v[8:9], v[8:9], v[4:5]
	v_cvt_pk_bf16_f32 v180, v6, v7
	v_cvt_pk_bf16_f32 v181, v8, v9
	v_add_u32_e32 v246, 0xbb000, v245
	global_store_dwordx4 v246, v[178:181], s[0:1]
	s_branch .Lmy_p1b_done
.Lmy_p1b_bg:
	s_sub_i32 s0, s91, 16
	s_lshl_b32 s0, s0, 9
	v_add_u32_e32 v245, s0, v245
	v_readlane_b32 s0, v244, 49
	v_readlane_b32 s1, v244, 50
	s_nop 4
	v_cvt_pk_bf16_f32 v136, v126, v127
	v_cvt_pk_bf16_f32 v137, v128, v129
	v_cvt_pk_bf16_f32 v138, v118, v119
	v_cvt_pk_bf16_f32 v139, v120, v121
	global_store_dwordx4 v245, v[136:139], s[0:1]
	v_cvt_pk_bf16_f32 v140, v122, v123
	v_cvt_pk_bf16_f32 v141, v124, v125
	v_cvt_pk_bf16_f32 v142, v114, v115
	v_cvt_pk_bf16_f32 v143, v116, v117
	global_store_dwordx4 v245, v[140:143], s[0:1] offset:256
	v_add_u32_e32 v246, 0x11000, v245
	v_cvt_pk_bf16_f32 v158, v110, v111
	v_cvt_pk_bf16_f32 v159, v112, v113
	v_cvt_pk_bf16_f32 v160, v102, v103
	v_cvt_pk_bf16_f32 v161, v104, v105
	global_store_dwordx4 v246, v[158:161], s[0:1]
	v_cvt_pk_bf16_f32 v162, v106, v107
	v_cvt_pk_bf16_f32 v163, v108, v109
	v_cvt_pk_bf16_f32 v164, v98, v99
	v_cvt_pk_bf16_f32 v165, v100, v101
	global_store_dwordx4 v246, v[162:165], s[0:1] offset:256
	v_add_u32_e32 v255, 0x22000, v245
	v_cvt_pk_bf16_f32 v166, v94, v95
	v_cvt_pk_bf16_f32 v167, v96, v97
	v_cvt_pk_bf16_f32 v168, v86, v87
	v_cvt_pk_bf16_f32 v169, v88, v89
	global_store_dwordx4 v255, v[166:169], s[0:1]
	v_cvt_pk_bf16_f32 v170, v90, v91
	v_cvt_pk_bf16_f32 v171, v92, v93
	v_cvt_pk_bf16_f32 v172, v82, v83
	v_cvt_pk_bf16_f32 v173, v84, v85
	global_store_dwordx4 v255, v[170:173], s[0:1] offset:256
	v_add_u32_e32 v246, 0x33000, v245
	v_cvt_pk_bf16_f32 v174, v78, v79
	v_cvt_pk_bf16_f32 v175, v80, v81
	v_cvt_pk_bf16_f32 v176, v70, v71
	v_cvt_pk_bf16_f32 v177, v72, v73
	global_store_dwordx4 v246, v[174:177], s[0:1]
	v_cvt_pk_bf16_f32 v178, v74, v75
	v_cvt_pk_bf16_f32 v179, v76, v77
	v_cvt_pk_bf16_f32 v180, v66, v67
	v_cvt_pk_bf16_f32 v181, v68, v69
	global_store_dwordx4 v246, v[178:181], s[0:1] offset:256
	v_add_u32_e32 v255, 0x88000, v245
	v_cvt_pk_bf16_f32 v182, v62, v63
	v_cvt_pk_bf16_f32 v183, v64, v65
	v_cvt_pk_bf16_f32 v184, v54, v55
	v_cvt_pk_bf16_f32 v185, v56, v57
	global_store_dwordx4 v255, v[182:185], s[0:1]
	v_cvt_pk_bf16_f32 v186, v58, v59
	v_cvt_pk_bf16_f32 v187, v60, v61
	v_cvt_pk_bf16_f32 v188, v50, v51
	v_cvt_pk_bf16_f32 v189, v52, v53
	global_store_dwordx4 v255, v[186:189], s[0:1] offset:256
	v_add_u32_e32 v246, 0x99000, v245
	v_cvt_pk_bf16_f32 v190, v46, v47
	v_cvt_pk_bf16_f32 v191, v48, v49
	v_cvt_pk_bf16_f32 v192, v38, v39
	v_cvt_pk_bf16_f32 v193, v40, v41
	global_store_dwordx4 v246, v[190:193], s[0:1]
	v_cvt_pk_bf16_f32 v194, v42, v43
	v_cvt_pk_bf16_f32 v195, v44, v45
	v_cvt_pk_bf16_f32 v196, v34, v35
	v_cvt_pk_bf16_f32 v197, v36, v37
	global_store_dwordx4 v246, v[194:197], s[0:1] offset:256
	v_add_u32_e32 v255, 0xaa000, v245
	v_cvt_pk_bf16_f32 v198, v30, v31
	v_cvt_pk_bf16_f32 v199, v32, v33
	v_cvt_pk_bf16_f32 v200, v22, v23
	v_cvt_pk_bf16_f32 v201, v24, v25
	global_store_dwordx4 v255, v[198:201], s[0:1]
	v_cvt_pk_bf16_f32 v202, v26, v27
	v_cvt_pk_bf16_f32 v203, v28, v29
	v_cvt_pk_bf16_f32 v204, v18, v19
	v_cvt_pk_bf16_f32 v205, v20, v21
	global_store_dwordx4 v255, v[202:205], s[0:1] offset:256
	v_add_u32_e32 v246, 0xbb000, v245
	v_cvt_pk_bf16_f32 v206, v14, v15
	v_cvt_pk_bf16_f32 v207, v16, v17
	v_cvt_pk_bf16_f32 v208, v6, v7
	v_cvt_pk_bf16_f32 v209, v8, v9
	global_store_dwordx4 v246, v[206:209], s[0:1]
	v_cvt_pk_bf16_f32 v210, v10, v11
	v_cvt_pk_bf16_f32 v211, v12, v13
	v_cvt_pk_bf16_f32 v212, v2, v3
	v_cvt_pk_bf16_f32 v213, v4, v5
	global_store_dwordx4 v246, v[210:213], s[0:1] offset:256

; #define GAS __attribute__((address_space(1)))
; __device__ __forceinline__ unsigned cvt_pk_bf16(float lo, float hi) { unsigned r; asm volatile("v_cvt_pk_bf16_f32 %0, %1, %2" : "=v"(r) : "v"(lo), "v"(hi)); return r; }
; __device__ __forceinline__ float bf_lo(unsigned w) { return __uint_as_float(w << 16); }
; __device__ __forceinline__ float bf_hi(unsigned w) { return __uint_as_float(w & 0xffff0000u); }
; __global__ void __launch_bounds__(NWAVES * 64, 2) fwd_kernel(Args args) {
;     ...
;         for (size_t i = (size_t)vcu * 512 + tid; i < (size_t)(MTOK / 4) * (CWID / 8); i += (size_t)G * 512) {
;             const int rq = (int)(i >> 8), ch = (int)(i & 255), row0 = rq * 4; const bool first = (row0 % SEQ) == 0;
;             const u32x4 z4 = (u32x4){0u, 0u, 0u, 0u};
;             u32x4 cv[6], bg[4];
; #pragma unroll
;             for (int r = 0; r < 6; ++r) cv[r] = (first && r < 2) ? z4 : *(const GAS u32x4*)(CH + (size_t)(row0 - 2 + r) * CWID + ch * 8);
; #pragma unroll
;             for (int r = 0; r < 4; ++r) bg[r] = *(const GAS u32x4*)(BG + (size_t)(row0 + r) * CWID + ch * 8);
;             float w0[8], w1[8], w2[8];
; #pragma unroll
;             for (int h = 0; h < 2; ++h) { const f32x4 a = *(const GAS f32x4*)(conv_b_w + ch * 8 + 4 * h), b = *(const GAS f32x4*)(conv_b_w + CWID + ch * 8 + 4 * h), c = *(const GAS f32x4*)(conv_b_w + 2 * CWID + ch * 8 + 4 * h);
; #pragma unroll
;                 for (int e = 0; e < 4; ++e) { w0[4 * h + e] = a[e]; w1[4 * h + e] = b[e]; w2[4 * h + e] = c[e]; } }
; #pragma unroll
;             for (int r = 0; r < 4; ++r) { unsigned ow[4];
; #pragma unroll
;                 for (int p_ = 0; p_ < 4; ++p_) {
;                     const float lo_ = bf_lo(bg[r][p_]) * (w0[2 * p_] * bf_lo(cv[r][p_]) + w1[2 * p_] * bf_lo(cv[r + 1][p_]) + w2[2 * p_] * bf_lo(cv[r + 2][p_]));
;                     const float hi_ = bf_hi(bg[r][p_]) * (w0[2 * p_ + 1] * bf_hi(cv[r][p_]) + w1[2 * p_ + 1] * bf_hi(cv[r + 1][p_]) + w2[2 * p_ + 1] * bf_hi(cv[r + 2][p_]));
;                     ow[p_] = cvt_pk_bf16(lo_, hi_); }
;                 *(GAS u32x4*)(MIX + (size_t)(row0 + r) * DM + CWID + ch * 8) = (u32x4){ow[0], ow[1], ow[2], ow[3]}; }
.LBB0_655:
	s_or_b64 exec, exec, s[14:15]
	v_lshl_add_u64 v[10:11], v[48:49], 0, v[44:45]
	global_load_dwordx4 v[18:21], v[54:55], off
	global_load_dwordx4 v[14:17], v[50:51], off
	global_load_dwordx4 v[6:9], v[54:55], off offset:16
	global_load_dwordx4 v[2:5], v[50:51], off offset:16
	v_lshl_add_u64 v[32:33], v[46:47], 0, v[44:45]
	global_load_dwordx4 v[84:87], v[10:11], off
	global_load_dwordx4 v[88:91], v[32:33], off
	v_or_b32_e32 v122, 1, v82
	v_add_co_u32_e32 v10, vcc, 0x1100, v32
	v_mul_u32_u24_e32 v44, 0x1100, v122
	v_lshl_add_u64 v[12:13], v[48:49], 0, v[44:45]
	v_addc_co_u32_e32 v11, vcc, 0, v33, vcc
	global_load_dwordx4 v[92:95], v[12:13], off
	global_load_dwordx4 v[96:99], v[10:11], off
	global_load_dwordx4 v[22:25], v[52:53], off
	s_nop 0
	global_load_dwordx4 v[10:13], v[52:53], off offset:16
	v_or_b32_e32 v123, 3, v30
	v_mov_b32_e32 v31, v45
	v_or_b32_e32 v124, 2, v82
	s_waitcnt vmcnt(10)
	v_lshlrev_b32_e32 v77, 16, v26
	v_and_b32_e32 v75, 0xffff0000, v26
	v_mul_u32_u24_e32 v30, 0x1100, v123
	v_add_co_u32_e32 v26, vcc, 0x2200, v32
	v_lshlrev_b32_e32 v73, 16, v27
	v_and_b32_e32 v69, 0xffff0000, v27
	v_lshl_add_u64 v[34:35], v[46:47], 0, v[30:31]
	v_mul_u32_u24_e32 v44, 0x1100, v124
	v_lshl_add_u64 v[36:37], v[48:49], 0, v[30:31]
	v_addc_co_u32_e32 v27, vcc, 0, v33, vcc
	v_lshlrev_b32_e32 v65, 16, v28
	v_and_b32_e32 v63, 0xffff0000, v28
	v_lshlrev_b32_e32 v61, 16, v29
	v_and_b32_e32 v59, 0xffff0000, v29
	v_lshl_add_u64 v[66:67], v[48:49], 0, v[44:45]
	global_load_dwordx4 v[26:29], v[26:27], off
	s_nop 0
	global_load_dwordx4 v[30:33], v[34:35], off
	global_load_dwordx4 v[100:103], v[66:67], off
	s_nop 0
	global_load_dwordx4 v[34:37], v[36:37], off
	v_lshlrev_b32_e32 v121, 16, v38
	v_lshlrev_b32_e32 v44, 13, v82
	v_lshl_add_u64 v[82:83], s[60:61], 0, v[44:45]
	v_lshl_add_u64 v[82:83], v[82:83], 0, v[56:57]
	v_add_co_u32_e32 v82, vcc, s6, v82
	v_lshl_add_u64 v[42:43], v[42:43], 0, s[4:5]
	s_nop 0
	v_addc_co_u32_e32 v83, vcc, 0, v83, vcc
	s_waitcnt vmcnt(13)
	v_mov_b32_e32 v104, v18
	s_waitcnt vmcnt(12)
	v_mov_b32_e32 v105, v14
	s_waitcnt vmcnt(11)
	v_mov_b32_e32 v70, v8
	s_waitcnt vmcnt(10)
	v_mov_b32_e32 v71, v4
	s_waitcnt vmcnt(9)
	v_lshlrev_b32_e32 v125, 16, v84
	s_waitcnt vmcnt(8)
	v_lshlrev_b32_e32 v76, 16, v88
	v_and_b32_e32 v126, 0xffff0000, v84
	v_lshlrev_b32_e32 v127, 16, v85
	v_and_b32_e32 v128, 0xffff0000, v85
	v_lshlrev_b32_e32 v60, 16, v91
	v_pk_mul_f32 v[84:85], v[104:105], v[76:77]
	v_pk_mul_f32 v[116:117], v[70:71], v[60:61]
	s_waitcnt vmcnt(6)
	v_lshlrev_b32_e32 v120, 16, v96
	s_waitcnt vmcnt(5)
	v_fma_f32 v61, v22, v121, v85
	v_mov_b32_e32 v106, v19
	v_mov_b32_e32 v107, v15
	v_mov_b32_e32 v80, v6
	v_mov_b32_e32 v81, v2
	v_and_b32_e32 v74, 0xffff0000, v88
	v_lshlrev_b32_e32 v64, 16, v90
	v_add_f32_e32 v61, v84, v61
	v_pk_mul_f32 v[84:85], v[104:105], v[120:121]
	v_lshlrev_b32_e32 v129, 16, v86
	v_and_b32_e32 v130, 0xffff0000, v86
	v_lshlrev_b32_e32 v131, 16, v87
	v_and_b32_e32 v132, 0xffff0000, v87
	v_pk_mul_f32 v[86:87], v[106:107], v[74:75]
	v_pk_mul_f32 v[112:113], v[80:81], v[64:65]
	v_fma_f32 v65, v22, v76, v85
	v_and_b32_e32 v85, 0xffff0000, v38
	v_fma_f32 v38, v23, v85, v87
	v_add_f32_e32 v65, v84, v65
	v_and_b32_e32 v84, 0xffff0000, v96
	v_add_f32_e32 v38, v86, v38
	v_mov_b32_e32 v108, v20
	v_mov_b32_e32 v109, v16
	v_lshlrev_b32_e32 v72, 16, v89
	v_mul_f32_e32 v61, v61, v125
	v_mul_f32_e32 v38, v38, v126
	v_pk_mul_f32 v[86:87], v[106:107], v[84:85]
	v_and_b32_e32 v68, 0xffff0000, v89
	v_pk_mul_f32 v[88:89], v[108:109], v[72:73]
	v_cvt_pk_bf16_f32 v38, v61, v38
	v_fma_f32 v61, v23, v74, v87
	v_lshlrev_b32_e32 v87, 16, v39
	v_add_f32_e32 v61, v86, v61
	v_lshlrev_b32_e32 v86, 16, v97
	v_fma_f32 v73, v24, v87, v89
	v_mov_b32_e32 v110, v21
	v_mov_b32_e32 v111, v17
	v_add_f32_e32 v73, v88, v73
	v_pk_mul_f32 v[88:89], v[108:109], v[86:87]
	v_and_b32_e32 v62, 0xffff0000, v90
	v_and_b32_e32 v58, 0xffff0000, v91
	v_pk_mul_f32 v[90:91], v[110:111], v[68:69]
	v_fma_f32 v77, v24, v72, v89
	v_and_b32_e32 v89, 0xffff0000, v39
	v_fma_f32 v39, v25, v89, v91
	v_add_f32_e32 v77, v88, v77
	v_and_b32_e32 v88, 0xffff0000, v97
	v_add_f32_e32 v39, v90, v39
	v_lshlrev_b32_e32 v44, 16, v92
	v_mul_f32_e32 v73, v73, v127
	v_mul_f32_e32 v39, v39, v128
	v_pk_mul_f32 v[90:91], v[110:111], v[88:89]
	v_mul_f32_e32 v44, v65, v44
	v_and_b32_e32 v65, 0xffff0000, v92
	v_cvt_pk_bf16_f32 v39, v73, v39
	v_fma_f32 v73, v25, v68, v91
	v_mul_f32_e32 v61, v61, v65
	v_lshlrev_b32_e32 v65, 16, v93
	v_add_f32_e32 v73, v90, v73
	v_lshlrev_b32_e32 v91, 16, v40
	v_lshlrev_b32_e32 v90, 16, v98
	v_mov_b32_e32 v78, v7
	v_mov_b32_e32 v79, v3
	v_mul_f32_e32 v65, v77, v65
	v_and_b32_e32 v77, 0xffff0000, v93
	v_pk_mul_f32 v[92:93], v[80:81], v[90:91]
	v_pk_mul_f32 v[114:115], v[78:79], v[62:63]
	s_waitcnt vmcnt(4)
	v_fma_f32 v87, v10, v64, v93
	v_and_b32_e32 v93, 0xffff0000, v40
	v_fma_f32 v85, v10, v91, v113
	v_fma_f32 v40, v11, v93, v115
	v_add_f32_e32 v85, v112, v85
	v_add_f32_e32 v87, v92, v87
	v_and_b32_e32 v92, 0xffff0000, v98
	v_add_f32_e32 v40, v114, v40
	v_mul_f32_e32 v85, v85, v129
	v_mul_f32_e32 v40, v40, v130
	v_pk_mul_f32 v[96:97], v[78:79], v[92:93]
	v_cvt_pk_bf16_f32 v40, v85, v40
	v_mul_f32_e32 v73, v73, v77
	v_fma_f32 v85, v11, v62, v97
	v_add_f32_e32 v85, v96, v85
	v_lshlrev_b32_e32 v96, 16, v99
	v_lshlrev_b32_e32 v97, 16, v41
	v_lshlrev_b32_e32 v77, 16, v94
	v_pk_mul_f32 v[112:113], v[70:71], v[96:97]
	v_mul_f32_e32 v77, v87, v77
	v_and_b32_e32 v87, 0xffff0000, v94
	v_fma_f32 v91, v12, v60, v113
	v_mov_b32_e32 v66, v9
	v_mov_b32_e32 v67, v5
	v_mul_f32_e32 v85, v85, v87
	v_lshlrev_b32_e32 v87, 16, v95
	v_add_f32_e32 v91, v112, v91
	v_pk_mul_f32 v[118:119], v[66:67], v[58:59]
	v_mul_f32_e32 v87, v91, v87
	v_and_b32_e32 v91, 0xffff0000, v95
	v_and_b32_e32 v95, 0xffff0000, v41
	v_fma_f32 v41, v13, v95, v119
	v_fma_f32 v89, v12, v97, v117
	v_add_f32_e32 v41, v118, v41
	v_add_f32_e32 v89, v116, v89
	v_and_b32_e32 v94, 0xffff0000, v99
	v_mul_f32_e32 v41, v41, v132
	v_mul_f32_e32 v89, v89, v131
	v_cvt_pk_bf16_f32 v41, v89, v41
	global_store_dwordx4 v[82:83], v[38:41], off
	v_pk_mul_f32 v[82:83], v[66:67], v[94:95]
	s_waitcnt vmcnt(2)
; #define GAS __attribute__((address_space(1)))
; __device__ __forceinline__ unsigned cvt_pk_bf16(float lo, float hi) { unsigned r; asm volatile("v_cvt_pk_bf16_f32 %0, %1, %2" : "=v"(r) : "v"(lo), "v"(hi)); return r; }
; __device__ __forceinline__ float bf_lo(unsigned w) { return __uint_as_float(w << 16); }
; __device__ __forceinline__ float bf_hi(unsigned w) { return __uint_as_float(w & 0xffff0000u); }
; __global__ void __launch_bounds__(NWAVES * 64, 2) fwd_kernel(Args args) {
;     ...
;         for (size_t i = (size_t)vcu * 512 + tid; i < (size_t)(MTOK / 4) * (CWID / 8); i += (size_t)G * 512) {
;             const int rq = (int)(i >> 8), ch = (int)(i & 255), row0 = rq * 4; const bool first = (row0 % SEQ) == 0;
;             const u32x4 z4 = (u32x4){0u, 0u, 0u, 0u};
;             u32x4 cv[6], bg[4];
; #pragma unroll
;             for (int r = 0; r < 6; ++r) cv[r] = (first && r < 2) ? z4 : *(const GAS u32x4*)(CH + (size_t)(row0 - 2 + r) * CWID + ch * 8);
; #pragma unroll
;             for (int r = 0; r < 4; ++r) bg[r] = *(const GAS u32x4*)(BG + (size_t)(row0 + r) * CWID + ch * 8);
;             float w0[8], w1[8], w2[8];
; #pragma unroll
;             for (int h = 0; h < 2; ++h) { const f32x4 a = *(const GAS f32x4*)(conv_b_w + ch * 8 + 4 * h), b = *(const GAS f32x4*)(conv_b_w + CWID + ch * 8 + 4 * h), c = *(const GAS f32x4*)(conv_b_w + 2 * CWID + ch * 8 + 4 * h);
; #pragma unroll
;                 for (int e = 0; e < 4; ++e) { w0[4 * h + e] = a[e]; w1[4 * h + e] = b[e]; w2[4 * h + e] = c[e]; } }
; #pragma unroll
;             for (int r = 0; r < 4; ++r) { unsigned ow[4];
; #pragma unroll
;                 for (int p_ = 0; p_ < 4; ++p_) {
;                     const float lo_ = bf_lo(bg[r][p_]) * (w0[2 * p_] * bf_lo(cv[r][p_]) + w1[2 * p_] * bf_lo(cv[r + 1][p_]) + w2[2 * p_] * bf_lo(cv[r + 2][p_]));
;                     const float hi_ = bf_hi(bg[r][p_]) * (w0[2 * p_ + 1] * bf_hi(cv[r][p_]) + w1[2 * p_ + 1] * bf_hi(cv[r + 1][p_]) + w2[2 * p_ + 1] * bf_hi(cv[r + 2][p_]));
;                     ow[p_] = cvt_pk_bf16(lo_, hi_); }
;                 *(GAS u32x4*)(MIX + (size_t)(row0 + r) * DM + CWID + ch * 8) = (u32x4){ow[0], ow[1], ow[2], ow[3]}; }
	v_and_b32_e32 v89, 0xffff0000, v103
	v_cvt_pk_bf16_f32 v38, v44, v61
	v_fma_f32 v41, v13, v58, v83
	v_lshlrev_b32_e32 v44, 13, v122
	v_add_f32_e32 v41, v82, v41
	v_lshl_add_u64 v[82:83], s[60:61], 0, v[44:45]
	v_lshl_add_u64 v[82:83], v[82:83], 0, v[56:57]
	v_mul_f32_e32 v41, v41, v91
	v_add_co_u32_e32 v82, vcc, s6, v82
	v_cvt_pk_bf16_f32 v39, v65, v73
	v_cvt_pk_bf16_f32 v40, v77, v85
	v_cvt_pk_bf16_f32 v41, v87, v41
	v_lshlrev_b32_e32 v61, 16, v100
	s_nop 0
	v_addc_co_u32_e32 v83, vcc, 0, v83, vcc
	global_store_dwordx4 v[82:83], v[38:41], off
	v_lshlrev_b32_e32 v44, 13, v124
	v_lshlrev_b32_e32 v73, 16, v101
	v_lshlrev_b32_e32 v41, 16, v26
	v_lshlrev_b32_e32 v40, 16, v30
	v_pk_mov_b32 v[76:77], v[40:41], v[76:77] op_sel:[1,0]
	v_lshl_add_u64 v[38:39], s[60:61], 0, v[44:45]
	v_pk_mul_f32 v[76:77], v[104:105], v[76:77]
	s_waitcnt vmcnt(2)
	v_lshlrev_b32_e32 v44, 16, v34
	v_fma_f32 v77, v22, v120, v77
	v_add_f32_e32 v76, v76, v77
	v_mul_f32_e32 v61, v76, v61
	v_mov_b32_e32 v76, v18
	v_mov_b32_e32 v77, v22
	v_pk_mul_f32 v[40:41], v[76:77], v[40:41]
	v_mov_b32_e32 v22, v19
	v_fma_f32 v14, v14, v120, v41
	v_add_f32_e32 v14, v40, v14
	v_and_b32_e32 v41, 0xffff0000, v26
	v_and_b32_e32 v40, 0xffff0000, v30
	v_pk_mul_f32 v[18:19], v[22:23], v[40:41]
	v_pk_mov_b32 v[74:75], v[40:41], v[74:75] op_sel:[1,0]
	v_fma_f32 v15, v15, v84, v19
	v_pk_mul_f32 v[74:75], v[106:107], v[74:75]
	v_add_f32_e32 v15, v18, v15
	v_lshlrev_b32_e32 v19, 16, v27
	v_lshlrev_b32_e32 v18, 16, v31
	v_mul_f32_e32 v44, v14, v44
	v_fma_f32 v14, v23, v84, v75
	v_pk_mov_b32 v[22:23], v[18:19], v[72:73] op_sel:[1,0]
	v_and_b32_e32 v34, 0xffff0000, v34
	v_pk_mul_f32 v[22:23], v[108:109], v[22:23]
	v_mul_f32_e32 v26, v15, v34
	v_fma_f32 v23, v24, v86, v23
	v_add_f32_e32 v22, v22, v23
	v_mul_f32_e32 v30, v22, v73
	v_mov_b32_e32 v22, v20
	v_mov_b32_e32 v23, v24
	v_pk_mul_f32 v[18:19], v[22:23], v[18:19]
	v_mov_b32_e32 v24, v21
	v_fma_f32 v16, v16, v86, v19
	v_add_f32_e32 v16, v18, v16
	v_and_b32_e32 v19, 0xffff0000, v27
	v_and_b32_e32 v18, 0xffff0000, v31
	v_pk_mov_b32 v[22:23], v[18:19], v[68:69] op_sel:[1,0]
	v_pk_mul_f32 v[18:19], v[24:25], v[18:19]
	v_lshlrev_b32_e32 v15, 16, v35
	v_fma_f32 v17, v17, v88, v19
	v_mul_f32_e32 v20, v16, v15
	v_and_b32_e32 v16, 0xffff0000, v35
	v_add_f32_e32 v17, v18, v17
	v_and_b32_e32 v65, 0xffff0000, v100
	v_mul_f32_e32 v21, v17, v16
	v_lshlrev_b32_e32 v17, 16, v28
	v_lshlrev_b32_e32 v16, 16, v32
	v_pk_mov_b32 v[18:19], v[16:17], v[64:65] op_sel:[1,0]
	v_lshlrev_b32_e32 v83, 16, v102
	v_pk_mul_f32 v[18:19], v[80:81], v[18:19]
	v_pk_mul_f32 v[22:23], v[110:111], v[22:23]
	v_fma_f32 v19, v10, v90, v19
	v_add_f32_e32 v18, v18, v19
	v_fma_f32 v15, v25, v88, v23
	v_mul_f32_e32 v23, v18, v83
	v_mov_b32_e32 v18, v6
	v_mov_b32_e32 v19, v10
	v_pk_mul_f32 v[16:17], v[18:19], v[16:17]
	v_and_b32_e32 v19, 0xffff0000, v28
	v_fma_f32 v2, v2, v90, v17
	v_and_b32_e32 v18, 0xffff0000, v32
	v_add_f32_e32 v2, v16, v2
	v_pk_mov_b32 v[16:17], v[18:19], v[62:63] op_sel:[1,0]
	v_and_b32_e32 v82, 0xffff0000, v101
	v_pk_mul_f32 v[16:17], v[78:79], v[16:17]
	v_and_b32_e32 v85, 0xffff0000, v102
	v_fma_f32 v6, v11, v92, v17
	v_add_f32_e32 v14, v74, v14
	v_add_f32_e32 v15, v22, v15
	v_add_f32_e32 v6, v16, v6
	v_mul_f32_e32 v14, v14, v65
	v_mul_f32_e32 v15, v15, v82
	v_mul_f32_e32 v6, v6, v85
	v_mov_b32_e32 v10, v7
	v_cvt_pk_bf16_f32 v14, v61, v14
	v_cvt_pk_bf16_f32 v15, v30, v15
	v_cvt_pk_bf16_f32 v16, v23, v6
	v_pk_mul_f32 v[6:7], v[10:11], v[18:19]
	v_lshlrev_b32_e32 v22, 16, v36
	v_fma_f32 v3, v3, v92, v7
	v_mul_f32_e32 v22, v2, v22
	v_and_b32_e32 v2, 0xffff0000, v36
	v_add_f32_e32 v3, v6, v3
	v_mul_f32_e32 v10, v3, v2
	v_lshlrev_b32_e32 v3, 16, v29
	v_lshlrev_b32_e32 v2, 16, v33
	v_pk_mov_b32 v[6:7], v[2:3], v[60:61] op_sel:[1,0]
	v_lshlrev_b32_e32 v87, 16, v103
	v_pk_mul_f32 v[6:7], v[70:71], v[6:7]
	v_lshlrev_b32_e32 v11, 16, v37
	v_fma_f32 v7, v12, v96, v7
	v_add_f32_e32 v6, v6, v7
	v_mul_f32_e32 v17, v6, v87
	v_mov_b32_e32 v6, v8
	v_mov_b32_e32 v7, v12
	v_pk_mul_f32 v[2:3], v[6:7], v[2:3]
	v_and_b32_e32 v7, 0xffff0000, v29
	v_fma_f32 v3, v4, v96, v3
	v_add_f32_e32 v2, v2, v3
	v_and_b32_e32 v6, 0xffff0000, v33
	v_mul_f32_e32 v8, v2, v11
	v_pk_mov_b32 v[2:3], v[6:7], v[58:59] op_sel:[1,0]
	v_lshl_add_u64 v[38:39], v[38:39], 0, v[56:57]
	v_pk_mul_f32 v[2:3], v[66:67], v[2:3]
	v_mov_b32_e32 v12, v9
	v_fma_f32 v3, v13, v94, v3
	v_add_f32_e32 v2, v2, v3
	v_mul_f32_e32 v2, v2, v89
	v_cvt_pk_bf16_f32 v17, v17, v2
	v_add_co_u32_e32 v2, vcc, s6, v38
	v_pk_mul_f32 v[6:7], v[12:13], v[6:7]
	s_nop 0
	v_addc_co_u32_e32 v3, vcc, 0, v39, vcc
	global_store_dwordx4 v[2:3], v[14:17], off
	v_cvt_pk_bf16_f32 v2, v44, v26
	v_fma_f32 v5, v5, v94, v7
	v_lshlrev_b32_e32 v44, 13, v123
	v_add_f32_e32 v5, v6, v5
	v_lshl_add_u64 v[6:7], s[60:61], 0, v[44:45]
	v_lshl_add_u64 v[6:7], v[6:7], 0, v[56:57]
	v_add_co_u32_e32 v6, vcc, 0x1000, v6
	v_and_b32_e32 v11, 0xffff0000, v37
	s_nop 0
	v_addc_co_u32_e32 v7, vcc, 0, v7, vcc
	v_cmp_lt_u64_e32 vcc, s[52:53], v[42:43]
	v_mul_f32_e32 v5, v5, v11
	s_or_b64 s[10:11], vcc, s[10:11]
	v_cvt_pk_bf16_f32 v3, v20, v21
	v_cvt_pk_bf16_f32 v4, v22, v10
	v_cvt_pk_bf16_f32 v5, v8, v5
	global_store_dwordx4 v[6:7], v[2:5], off
	s_andn2_b64 exec, exec, s[10:11]
	s_cbranch_execz .LBB0_660
.LBB0_656:
	v_lshrrev_b32_e32 v30, 6, v42
	v_and_b32_e32 v82, 0x3ffc, v30
	v_and_b32_e32 v2, 0x3ff00, v42
	v_cmp_ne_u32_e64 s[0:1], 0, v2
	v_mul_u32_u24_e32 v44, 0x1100, v82
	v_mov_b32_e32 v26, 0
	v_mov_b32_e32 v27, 0
	v_mov_b32_e32 v28, 0
	v_mov_b32_e32 v29, 0
	s_and_saveexec_b64 s[14:15], s[0:1]
	s_cbranch_execz .LBB0_658
	v_lshl_add_u64 v[2:3], v[46:47], 0, v[44:45]
	v_add_co_u32_e32 v2, vcc, 0xffffde00, v2
	s_nop 1
	v_addc_co_u32_e32 v3, vcc, -1, v3, vcc
	global_load_dwordx4 v[26:29], v[2:3], off
.LBB0_658:
	s_or_b64 exec, exec, s[14:15]
	v_mov_b32_e32 v38, 0
	v_mov_b32_e32 v39, 0
	v_mov_b32_e32 v40, 0
	v_mov_b32_e32 v41, 0
	s_and_saveexec_b64 s[14:15], s[0:1]
	s_cbranch_execz .LBB0_655
	v_lshl_add_u64 v[2:3], v[46:47], 0, v[44:45]
	v_add_co_u32_e32 v2, vcc, 0xffffef00, v2
	s_nop 1
	v_addc_co_u32_e32 v3, vcc, -1, v3, vcc
	global_load_dwordx4 v[38:41], v[2:3], off
	s_branch .LBB0_655

; __device__ __forceinline__ unsigned cvt_pk_bf16(float lo, float hi) { unsigned r; asm volatile("v_cvt_pk_bf16_f32 %0, %1, %2" : "=v"(r) : "v"(lo), "v"(hi)); return r; }
; __device__ __forceinline__ float bf_lo(unsigned w) { return __uint_as_float(w << 16); }
;     __device__ __forceinline__ void operator()(EPI_ARGS) const {
;     ...
;                 for (int bj = 0; bj < 2; ++bj) { const size_t off = (size_t)(row0 + ai * HALF + m * 16) * ldc + col0 + bj * HALF;
;                     if (RES_BF16) { const u32x4 rw = *(const u32x4*)((const bf16*)resid + off); r0[m][bj] = __builtin_bit_cast(f32x4, rw); }
;                     else { r0[m][bj] = *(const f32x4*)((const float*)resid + off); r1[m][bj] = *(const f32x4*)((const float*)resid + off + 4); } }
; #pragma unroll
;             for (int m = 0; m < 4; ++m) { const int row = row0 + ai * HALF + m * 16; const size_t off = (size_t)row * ldc + col0; float ss = 0.f, mx = 0.f;
; #pragma unroll
;                 for (int bj = 0; bj < 2; ++bj) {
;                     f32x4 a0, a1;
;                     if (RES_BF16) { const u32x4 rw = __builtin_bit_cast(u32x4, r0[m][bj]); a0 = (f32x4){bf_lo(rw.x), bf_hi(rw.x), bf_lo(rw.y), bf_hi(rw.y)}; a1 = (f32x4){bf_lo(rw.z), bf_hi(rw.z), bf_lo(rw.w), bf_hi(rw.w)};
;                         if (RES_SCALE) { const float rf = rfac[row]; a0 = a0 * rf; a1 = a1 * rf; } }
;                     else { a0 = r0[m][bj]; a1 = r1[m][bj]; }
;                     const f32x4 v0 = acc[ai][bj][m][0] + a0, v1 = acc[ai][bj][m][1] + a1;
;                     u32x4 w; w.x = cvt_pk_bf16(v0[0], v0[1]); w.y = cvt_pk_bf16(v0[2], v0[3]); w.z = cvt_pk_bf16(v1[0], v1[1]); w.w = cvt_pk_bf16(v1[2], v1[3]); *(u32x4*)(ob + off + bj * HALF) = w;
;                     ss += (v0[0] * v0[0] + v0[1] * v0[1]) + (v0[2] * v0[2] + v0[3] * v0[3]) + (v1[0] * v1[0] + v1[1] * v1[1]) + (v1[2] * v1[2] + v1[3] * v1[3]);
;                     if (rowmax) mx = fmaxf(mx, fmaxf(fmaxf(fmaxf(fabsf(v0[0]), fabsf(v0[1])), fmaxf(fabsf(v0[2]), fabsf(v0[3]))), fmaxf(fmaxf(fabsf(v1[0]), fabsf(v1[1])), fmaxf(fabsf(v1[2]), fabsf(v1[3]))))); }
;                 ss += __shfl_xor(ss, 16); ss += __shfl_xor(ss, 32); ssv[ai * 4 + m] = ss;
;                 if (rowmax) { mx = fmaxf(mx, __shfl_xor(mx, 16)); mx = fmaxf(mx, __shfl_xor(mx, 32)); } mxv[ai * 4 + m] = mx; }
.LBB0_1005:
	s_nop 7
	v_lshl_add_u32 v245, s72, 8, v181
	v_lshlrev_b32_e32 v245, 13, v245
	v_lshl_or_b32 v246, s70, 8, v182
	v_lshl_add_u32 v245, v246, 1, v245
	global_load_dwordx4 v[130:133], v245, s[52:53]
	global_load_dwordx4 v[134:137], v245, s[52:53] offset:256
	v_add_u32_e32 v246, 0x20000, v245
	global_load_dwordx4 v[138:141], v246, s[52:53]
	global_load_dwordx4 v[142:145], v246, s[52:53] offset:256
	v_add_u32_e32 v255, 0x40000, v245
	global_load_dwordx4 v[146:149], v255, s[52:53]
	global_load_dwordx4 v[150:153], v255, s[52:53] offset:256
	v_add_u32_e32 v246, 0x60000, v245
	global_load_dwordx4 v[154:157], v246, s[52:53]
	global_load_dwordx4 v[162:165], v246, s[52:53] offset:256
	v_add_u32_e32 v255, 0x100000, v245
	global_load_dwordx4 v[166:169], v255, s[52:53]
	global_load_dwordx4 v[170:173], v255, s[52:53] offset:256
	v_add_u32_e32 v246, 0x120000, v245
	global_load_dwordx4 v[190:193], v246, s[52:53]
	global_load_dwordx4 v[194:197], v246, s[52:53] offset:256
	v_add_u32_e32 v255, 0x140000, v245
	global_load_dwordx4 v[198:201], v255, s[52:53]
	global_load_dwordx4 v[202:205], v255, s[52:53] offset:256
	v_add_u32_e32 v246, 0x160000, v245
	global_load_dwordx4 v[206:209], v246, s[52:53]
	global_load_dwordx4 v[210:213], v246, s[52:53] offset:256
	v_lshl_add_u32 v245, s72, 8, v181
	v_mul_u32_u24_e32 v245, 0x2100, v245
	v_lshl_or_b32 v246, s70, 8, v182
	v_lshl_add_u32 v245, v246, 1, v245
	s_waitcnt vmcnt(15)
	v_lshlrev_b32_e32 v248, 16, v130
	v_and_b32_e32 v249, 0xffff0000, v130
	v_lshlrev_b32_e32 v250, 16, v131
	v_and_b32_e32 v251, 0xffff0000, v131
	v_pk_add_f32 v[126:127], v[126:127], v[248:249]
	v_pk_add_f32 v[128:129], v[128:129], v[250:251]
	v_lshlrev_b32_e32 v248, 16, v132
	v_and_b32_e32 v249, 0xffff0000, v132
	v_lshlrev_b32_e32 v250, 16, v133
	v_and_b32_e32 v251, 0xffff0000, v133
	v_pk_add_f32 v[122:123], v[122:123], v[248:249]
	v_pk_add_f32 v[124:125], v[124:125], v[250:251]
	v_cvt_pk_bf16_f32 v130, v126, v127
	v_cvt_pk_bf16_f32 v131, v128, v129
	v_cvt_pk_bf16_f32 v132, v122, v123
	v_cvt_pk_bf16_f32 v133, v124, v125
	global_store_dwordx4 v245, v[130:133], s[100:101]
	v_mul_f32_e32 v247, v126, v126
	v_fmac_f32_e32 v247, v127, v127
	v_fmac_f32_e32 v247, v128, v128
	v_fmac_f32_e32 v247, v129, v129
	v_mul_f32_e32 v254, v122, v122
	v_fmac_f32_e32 v254, v123, v123
	v_fmac_f32_e32 v254, v124, v124
	v_fmac_f32_e32 v254, v125, v125
	v_max3_f32 v252, |v126|, |v127|, |v128|
	v_max3_f32 v252, |v129|, |v122|, v252
	v_max3_f32 v252, |v123|, |v124|, v252
	v_max_f32_e64 v252, |v125|, v252
	s_waitcnt vmcnt(15)
	v_lshlrev_b32_e32 v248, 16, v134
	v_and_b32_e32 v249, 0xffff0000, v134
	v_lshlrev_b32_e32 v250, 16, v135
	v_and_b32_e32 v251, 0xffff0000, v135
	v_pk_add_f32 v[118:119], v[118:119], v[248:249]
	v_pk_add_f32 v[120:121], v[120:121], v[250:251]
	v_lshlrev_b32_e32 v248, 16, v136
	v_and_b32_e32 v249, 0xffff0000, v136
	v_lshlrev_b32_e32 v250, 16, v137
	v_and_b32_e32 v251, 0xffff0000, v137
	v_pk_add_f32 v[114:115], v[114:115], v[248:249]
	v_pk_add_f32 v[116:117], v[116:117], v[250:251]
	v_cvt_pk_bf16_f32 v134, v118, v119
	v_cvt_pk_bf16_f32 v135, v120, v121
	v_cvt_pk_bf16_f32 v136, v114, v115
	v_cvt_pk_bf16_f32 v137, v116, v117
	global_store_dwordx4 v245, v[134:137], s[100:101] offset:256
	v_fmac_f32_e32 v247, v118, v118
	v_fmac_f32_e32 v247, v119, v119
	v_fmac_f32_e32 v247, v120, v120
	v_fmac_f32_e32 v247, v121, v121
	v_fmac_f32_e32 v254, v114, v114
	v_fmac_f32_e32 v254, v115, v115
	v_fmac_f32_e32 v254, v116, v116
	v_fmac_f32_e32 v254, v117, v117
	v_max3_f32 v252, |v118|, |v119|, v252
	v_max_f32_e64 v252, |v120|, v252
	v_max3_f32 v252, |v121|, |v114|, v252
	v_max3_f32 v252, |v115|, |v116|, v252
	v_max_f32_e64 v252, |v117|, v252
	v_add_f32_e32 v126, v247, v254
	v_mov_b32_e32 v128, v252
	s_waitcnt vmcnt(15)
	v_lshlrev_b32_e32 v248, 16, v138
	v_and_b32_e32 v249, 0xffff0000, v138
	v_lshlrev_b32_e32 v250, 16, v139
	v_and_b32_e32 v251, 0xffff0000, v139
	v_pk_add_f32 v[110:111], v[110:111], v[248:249]
	v_pk_add_f32 v[112:113], v[112:113], v[250:251]
	v_lshlrev_b32_e32 v248, 16, v140
	v_and_b32_e32 v249, 0xffff0000, v140
	v_lshlrev_b32_e32 v250, 16, v141
	v_and_b32_e32 v251, 0xffff0000, v141
	v_pk_add_f32 v[106:107], v[106:107], v[248:249]
	v_pk_add_f32 v[108:109], v[108:109], v[250:251]
	v_cvt_pk_bf16_f32 v138, v110, v111
	v_cvt_pk_bf16_f32 v139, v112, v113
	v_cvt_pk_bf16_f32 v140, v106, v107
	v_cvt_pk_bf16_f32 v141, v108, v109
	v_add_u32_e32 v246, 0x21000, v245
	global_store_dwordx4 v246, v[138:141], s[100:101]
	v_mul_f32_e32 v247, v110, v110
	v_fmac_f32_e32 v247, v111, v111
	v_fmac_f32_e32 v247, v112, v112
	v_fmac_f32_e32 v247, v113, v113
	v_mul_f32_e32 v254, v106, v106
	v_fmac_f32_e32 v254, v107, v107
	v_fmac_f32_e32 v254, v108, v108
	v_fmac_f32_e32 v254, v109, v109
	v_max3_f32 v252, |v110|, |v111|, |v112|
	v_max3_f32 v252, |v113|, |v106|, v252
	v_max3_f32 v252, |v107|, |v108|, v252
	v_max_f32_e64 v252, |v109|, v252
	s_waitcnt vmcnt(15)
	v_lshlrev_b32_e32 v248, 16, v142
	v_and_b32_e32 v249, 0xffff0000, v142
	v_lshlrev_b32_e32 v250, 16, v143
	v_and_b32_e32 v251, 0xffff0000, v143
	v_pk_add_f32 v[102:103], v[102:103], v[248:249]
	v_pk_add_f32 v[104:105], v[104:105], v[250:251]
	v_lshlrev_b32_e32 v248, 16, v144
	v_and_b32_e32 v249, 0xffff0000, v144
	v_lshlrev_b32_e32 v250, 16, v145
	v_and_b32_e32 v251, 0xffff0000, v145
	v_pk_add_f32 v[98:99], v[98:99], v[248:249]
	v_pk_add_f32 v[100:101], v[100:101], v[250:251]
	v_cvt_pk_bf16_f32 v142, v102, v103
	v_cvt_pk_bf16_f32 v143, v104, v105
	v_cvt_pk_bf16_f32 v144, v98, v99
	v_cvt_pk_bf16_f32 v145, v100, v101
	v_add_u32_e32 v255, 0x21000, v245
	global_store_dwordx4 v255, v[142:145], s[100:101] offset:256
	v_fmac_f32_e32 v247, v102, v102
	v_fmac_f32_e32 v247, v103, v103
	v_fmac_f32_e32 v247, v104, v104
	v_fmac_f32_e32 v247, v105, v105
	v_fmac_f32_e32 v254, v98, v98
	v_fmac_f32_e32 v254, v99, v99
	v_fmac_f32_e32 v254, v100, v100
	v_fmac_f32_e32 v254, v101, v101
	v_max3_f32 v252, |v102|, |v103|, v252
	v_max_f32_e64 v252, |v104|, v252
	v_max3_f32 v252, |v105|, |v98|, v252
	v_max3_f32 v252, |v99|, |v100|, v252
	v_max_f32_e64 v252, |v101|, v252
	v_add_f32_e32 v110, v247, v254
	v_mov_b32_e32 v112, v252
	s_waitcnt vmcnt(15)
; __device__ __forceinline__ unsigned cvt_pk_bf16(float lo, float hi) { unsigned r; asm volatile("v_cvt_pk_bf16_f32 %0, %1, %2" : "=v"(r) : "v"(lo), "v"(hi)); return r; }
; __device__ __forceinline__ float bf_lo(unsigned w) { return __uint_as_float(w << 16); }
; __device__ __forceinline__ float bf_hi(unsigned w) { return __uint_as_float(w & 0xffff0000u); }
;     __device__ __forceinline__ void operator()(EPI_ARGS) const {
;     ...
;             for (int m = 0; m < 4; ++m) { const int row = row0 + ai * HALF + m * 16; const size_t off = (size_t)row * ldc + col0; float ss = 0.f, mx = 0.f;
; #pragma unroll
;                 for (int bj = 0; bj < 2; ++bj) {
;                     f32x4 a0, a1;
;                     if (RES_BF16) { const u32x4 rw = __builtin_bit_cast(u32x4, r0[m][bj]); a0 = (f32x4){bf_lo(rw.x), bf_hi(rw.x), bf_lo(rw.y), bf_hi(rw.y)}; a1 = (f32x4){bf_lo(rw.z), bf_hi(rw.z), bf_lo(rw.w), bf_hi(rw.w)};
;                         if (RES_SCALE) { const float rf = rfac[row]; a0 = a0 * rf; a1 = a1 * rf; } }
;                     else { a0 = r0[m][bj]; a1 = r1[m][bj]; }
;                     const f32x4 v0 = acc[ai][bj][m][0] + a0, v1 = acc[ai][bj][m][1] + a1;
;                     u32x4 w; w.x = cvt_pk_bf16(v0[0], v0[1]); w.y = cvt_pk_bf16(v0[2], v0[3]); w.z = cvt_pk_bf16(v1[0], v1[1]); w.w = cvt_pk_bf16(v1[2], v1[3]); *(u32x4*)(ob + off + bj * HALF) = w;
;                     ss += (v0[0] * v0[0] + v0[1] * v0[1]) + (v0[2] * v0[2] + v0[3] * v0[3]) + (v1[0] * v1[0] + v1[1] * v1[1]) + (v1[2] * v1[2] + v1[3] * v1[3]);
;                     if (rowmax) mx = fmaxf(mx, fmaxf(fmaxf(fmaxf(fabsf(v0[0]), fabsf(v0[1])), fmaxf(fabsf(v0[2]), fabsf(v0[3]))), fmaxf(fmaxf(fabsf(v1[0]), fabsf(v1[1])), fmaxf(fabsf(v1[2]), fabsf(v1[3]))))); }
;                 ss += __shfl_xor(ss, 16); ss += __shfl_xor(ss, 32); ssv[ai * 4 + m] = ss;
;                 if (rowmax) { mx = fmaxf(mx, __shfl_xor(mx, 16)); mx = fmaxf(mx, __shfl_xor(mx, 32)); } mxv[ai * 4 + m] = mx; }
	v_lshlrev_b32_e32 v248, 16, v146
	v_and_b32_e32 v249, 0xffff0000, v146
	v_lshlrev_b32_e32 v250, 16, v147
	v_and_b32_e32 v251, 0xffff0000, v147
	v_pk_add_f32 v[94:95], v[94:95], v[248:249]
	v_pk_add_f32 v[96:97], v[96:97], v[250:251]
	v_lshlrev_b32_e32 v248, 16, v148
	v_and_b32_e32 v249, 0xffff0000, v148
	v_lshlrev_b32_e32 v250, 16, v149
	v_and_b32_e32 v251, 0xffff0000, v149
	v_pk_add_f32 v[90:91], v[90:91], v[248:249]
	v_pk_add_f32 v[92:93], v[92:93], v[250:251]
	v_cvt_pk_bf16_f32 v146, v94, v95
	v_cvt_pk_bf16_f32 v147, v96, v97
	v_cvt_pk_bf16_f32 v148, v90, v91
	v_cvt_pk_bf16_f32 v149, v92, v93
	v_add_u32_e32 v246, 0x42000, v245
	global_store_dwordx4 v246, v[146:149], s[100:101]
	v_mul_f32_e32 v247, v94, v94
	v_fmac_f32_e32 v247, v95, v95
	v_fmac_f32_e32 v247, v96, v96
	v_fmac_f32_e32 v247, v97, v97
	v_mul_f32_e32 v254, v90, v90
	v_fmac_f32_e32 v254, v91, v91
	v_fmac_f32_e32 v254, v92, v92
	v_fmac_f32_e32 v254, v93, v93
	v_max3_f32 v252, |v94|, |v95|, |v96|
	v_max3_f32 v252, |v97|, |v90|, v252
	v_max3_f32 v252, |v91|, |v92|, v252
	v_max_f32_e64 v252, |v93|, v252
	s_waitcnt vmcnt(15)
	v_lshlrev_b32_e32 v248, 16, v150
	v_and_b32_e32 v249, 0xffff0000, v150
	v_lshlrev_b32_e32 v250, 16, v151
	v_and_b32_e32 v251, 0xffff0000, v151
	v_pk_add_f32 v[86:87], v[86:87], v[248:249]
	v_pk_add_f32 v[88:89], v[88:89], v[250:251]
	v_lshlrev_b32_e32 v248, 16, v152
	v_and_b32_e32 v249, 0xffff0000, v152
	v_lshlrev_b32_e32 v250, 16, v153
	v_and_b32_e32 v251, 0xffff0000, v153
	v_pk_add_f32 v[82:83], v[82:83], v[248:249]
	v_pk_add_f32 v[84:85], v[84:85], v[250:251]
	v_cvt_pk_bf16_f32 v150, v86, v87
	v_cvt_pk_bf16_f32 v151, v88, v89
	v_cvt_pk_bf16_f32 v152, v82, v83
	v_cvt_pk_bf16_f32 v153, v84, v85
	v_add_u32_e32 v255, 0x42000, v245
	global_store_dwordx4 v255, v[150:153], s[100:101] offset:256
	v_fmac_f32_e32 v247, v86, v86
	v_fmac_f32_e32 v247, v87, v87
	v_fmac_f32_e32 v247, v88, v88
	v_fmac_f32_e32 v247, v89, v89
	v_fmac_f32_e32 v254, v82, v82
	v_fmac_f32_e32 v254, v83, v83
	v_fmac_f32_e32 v254, v84, v84
	v_fmac_f32_e32 v254, v85, v85
	v_max3_f32 v252, |v86|, |v87|, v252
	v_max_f32_e64 v252, |v88|, v252
	v_max3_f32 v252, |v89|, |v82|, v252
	v_max3_f32 v252, |v83|, |v84|, v252
	v_max_f32_e64 v252, |v85|, v252
	v_add_f32_e32 v94, v247, v254
	v_mov_b32_e32 v96, v252
	s_waitcnt vmcnt(15)
	v_lshlrev_b32_e32 v248, 16, v154
	v_and_b32_e32 v249, 0xffff0000, v154
	v_lshlrev_b32_e32 v250, 16, v155
	v_and_b32_e32 v251, 0xffff0000, v155
	v_pk_add_f32 v[78:79], v[78:79], v[248:249]
	v_pk_add_f32 v[80:81], v[80:81], v[250:251]
	v_lshlrev_b32_e32 v248, 16, v156
	v_and_b32_e32 v249, 0xffff0000, v156
	v_lshlrev_b32_e32 v250, 16, v157
	v_and_b32_e32 v251, 0xffff0000, v157
	v_pk_add_f32 v[74:75], v[74:75], v[248:249]
	v_pk_add_f32 v[76:77], v[76:77], v[250:251]
	v_cvt_pk_bf16_f32 v154, v78, v79
	v_cvt_pk_bf16_f32 v155, v80, v81
	v_cvt_pk_bf16_f32 v156, v74, v75
	v_cvt_pk_bf16_f32 v157, v76, v77
	v_add_u32_e32 v246, 0x63000, v245
	global_store_dwordx4 v246, v[154:157], s[100:101]
	v_mul_f32_e32 v247, v78, v78
	v_fmac_f32_e32 v247, v79, v79
	v_fmac_f32_e32 v247, v80, v80
	v_fmac_f32_e32 v247, v81, v81
	v_mul_f32_e32 v254, v74, v74
	v_fmac_f32_e32 v254, v75, v75
	v_fmac_f32_e32 v254, v76, v76
	v_fmac_f32_e32 v254, v77, v77
	v_max3_f32 v252, |v78|, |v79|, |v80|
	v_max3_f32 v252, |v81|, |v74|, v252
	v_max3_f32 v252, |v75|, |v76|, v252
	v_max_f32_e64 v252, |v77|, v252
	s_waitcnt vmcnt(15)
	v_lshlrev_b32_e32 v248, 16, v162
	v_and_b32_e32 v249, 0xffff0000, v162
	v_lshlrev_b32_e32 v250, 16, v163
	v_and_b32_e32 v251, 0xffff0000, v163
	v_pk_add_f32 v[70:71], v[70:71], v[248:249]
	v_pk_add_f32 v[72:73], v[72:73], v[250:251]
	v_lshlrev_b32_e32 v248, 16, v164
	v_and_b32_e32 v249, 0xffff0000, v164
	v_lshlrev_b32_e32 v250, 16, v165
	v_and_b32_e32 v251, 0xffff0000, v165
	v_pk_add_f32 v[66:67], v[66:67], v[248:249]
	v_pk_add_f32 v[68:69], v[68:69], v[250:251]
	v_cvt_pk_bf16_f32 v162, v70, v71
	v_cvt_pk_bf16_f32 v163, v72, v73
	v_cvt_pk_bf16_f32 v164, v66, v67
	v_cvt_pk_bf16_f32 v165, v68, v69
	v_add_u32_e32 v255, 0x63000, v245
	global_store_dwordx4 v255, v[162:165], s[100:101] offset:256
	v_fmac_f32_e32 v247, v70, v70
	v_fmac_f32_e32 v247, v71, v71
	v_fmac_f32_e32 v247, v72, v72
	v_fmac_f32_e32 v247, v73, v73
	v_fmac_f32_e32 v254, v66, v66
	v_fmac_f32_e32 v254, v67, v67
	v_fmac_f32_e32 v254, v68, v68
	v_fmac_f32_e32 v254, v69, v69
	v_max3_f32 v252, |v70|, |v71|, v252
	v_max_f32_e64 v252, |v72|, v252
	v_max3_f32 v252, |v73|, |v66|, v252
	v_max3_f32 v252, |v67|, |v68|, v252
	v_max_f32_e64 v252, |v69|, v252
	v_add_f32_e32 v78, v247, v254
	v_mov_b32_e32 v80, v252
	s_waitcnt vmcnt(15)
	v_lshlrev_b32_e32 v248, 16, v166
	v_and_b32_e32 v249, 0xffff0000, v166
	v_lshlrev_b32_e32 v250, 16, v167
	v_and_b32_e32 v251, 0xffff0000, v167
	v_pk_add_f32 v[62:63], v[62:63], v[248:249]
	v_pk_add_f32 v[64:65], v[64:65], v[250:251]
	v_lshlrev_b32_e32 v248, 16, v168
	v_and_b32_e32 v249, 0xffff0000, v168
	v_lshlrev_b32_e32 v250, 16, v169
	v_and_b32_e32 v251, 0xffff0000, v169
	v_pk_add_f32 v[58:59], v[58:59], v[248:249]
	v_pk_add_f32 v[60:61], v[60:61], v[250:251]
	v_cvt_pk_bf16_f32 v166, v62, v63
	v_cvt_pk_bf16_f32 v167, v64, v65
	v_cvt_pk_bf16_f32 v168, v58, v59
	v_cvt_pk_bf16_f32 v169, v60, v61
	v_add_u32_e32 v246, 0x108000, v245
	global_store_dwordx4 v246, v[166:169], s[100:101]
	v_mul_f32_e32 v247, v62, v62
	v_fmac_f32_e32 v247, v63, v63
	v_fmac_f32_e32 v247, v64, v64
	v_fmac_f32_e32 v247, v65, v65
	v_mul_f32_e32 v254, v58, v58
	v_fmac_f32_e32 v254, v59, v59
	v_fmac_f32_e32 v254, v60, v60
	v_fmac_f32_e32 v254, v61, v61
	v_max3_f32 v252, |v62|, |v63|, |v64|
	v_max3_f32 v252, |v65|, |v58|, v252
	v_max3_f32 v252, |v59|, |v60|, v252
	v_max_f32_e64 v252, |v61|, v252
	s_waitcnt vmcnt(15)
; __device__ __forceinline__ unsigned cvt_pk_bf16(float lo, float hi) { unsigned r; asm volatile("v_cvt_pk_bf16_f32 %0, %1, %2" : "=v"(r) : "v"(lo), "v"(hi)); return r; }
; __device__ __forceinline__ float bf_lo(unsigned w) { return __uint_as_float(w << 16); }
; __device__ __forceinline__ float bf_hi(unsigned w) { return __uint_as_float(w & 0xffff0000u); }
;     __device__ __forceinline__ void operator()(EPI_ARGS) const {
;     ...
;             for (int m = 0; m < 4; ++m) { const int row = row0 + ai * HALF + m * 16; const size_t off = (size_t)row * ldc + col0; float ss = 0.f, mx = 0.f;
; #pragma unroll
;                 for (int bj = 0; bj < 2; ++bj) {
;                     f32x4 a0, a1;
;                     if (RES_BF16) { const u32x4 rw = __builtin_bit_cast(u32x4, r0[m][bj]); a0 = (f32x4){bf_lo(rw.x), bf_hi(rw.x), bf_lo(rw.y), bf_hi(rw.y)}; a1 = (f32x4){bf_lo(rw.z), bf_hi(rw.z), bf_lo(rw.w), bf_hi(rw.w)};
;                         if (RES_SCALE) { const float rf = rfac[row]; a0 = a0 * rf; a1 = a1 * rf; } }
;                     else { a0 = r0[m][bj]; a1 = r1[m][bj]; }
;                     const f32x4 v0 = acc[ai][bj][m][0] + a0, v1 = acc[ai][bj][m][1] + a1;
;                     u32x4 w; w.x = cvt_pk_bf16(v0[0], v0[1]); w.y = cvt_pk_bf16(v0[2], v0[3]); w.z = cvt_pk_bf16(v1[0], v1[1]); w.w = cvt_pk_bf16(v1[2], v1[3]); *(u32x4*)(ob + off + bj * HALF) = w;
;                     ss += (v0[0] * v0[0] + v0[1] * v0[1]) + (v0[2] * v0[2] + v0[3] * v0[3]) + (v1[0] * v1[0] + v1[1] * v1[1]) + (v1[2] * v1[2] + v1[3] * v1[3]);
;                     if (rowmax) mx = fmaxf(mx, fmaxf(fmaxf(fmaxf(fabsf(v0[0]), fabsf(v0[1])), fmaxf(fabsf(v0[2]), fabsf(v0[3]))), fmaxf(fmaxf(fabsf(v1[0]), fabsf(v1[1])), fmaxf(fabsf(v1[2]), fabsf(v1[3]))))); }
;                 ss += __shfl_xor(ss, 16); ss += __shfl_xor(ss, 32); ssv[ai * 4 + m] = ss;
;                 if (rowmax) { mx = fmaxf(mx, __shfl_xor(mx, 16)); mx = fmaxf(mx, __shfl_xor(mx, 32)); } mxv[ai * 4 + m] = mx; }
	v_lshlrev_b32_e32 v248, 16, v170
	v_and_b32_e32 v249, 0xffff0000, v170
	v_lshlrev_b32_e32 v250, 16, v171
	v_and_b32_e32 v251, 0xffff0000, v171
	v_pk_add_f32 v[54:55], v[54:55], v[248:249]
	v_pk_add_f32 v[56:57], v[56:57], v[250:251]
	v_lshlrev_b32_e32 v248, 16, v172
	v_and_b32_e32 v249, 0xffff0000, v172
	v_lshlrev_b32_e32 v250, 16, v173
	v_and_b32_e32 v251, 0xffff0000, v173
	v_pk_add_f32 v[50:51], v[50:51], v[248:249]
	v_pk_add_f32 v[52:53], v[52:53], v[250:251]
	v_cvt_pk_bf16_f32 v170, v54, v55
	v_cvt_pk_bf16_f32 v171, v56, v57
	v_cvt_pk_bf16_f32 v172, v50, v51
	v_cvt_pk_bf16_f32 v173, v52, v53
	v_add_u32_e32 v255, 0x108000, v245
	global_store_dwordx4 v255, v[170:173], s[100:101] offset:256
	v_fmac_f32_e32 v247, v54, v54
	v_fmac_f32_e32 v247, v55, v55
	v_fmac_f32_e32 v247, v56, v56
	v_fmac_f32_e32 v247, v57, v57
	v_fmac_f32_e32 v254, v50, v50
	v_fmac_f32_e32 v254, v51, v51
	v_fmac_f32_e32 v254, v52, v52
	v_fmac_f32_e32 v254, v53, v53
	v_max3_f32 v252, |v54|, |v55|, v252
	v_max_f32_e64 v252, |v56|, v252
	v_max3_f32 v252, |v57|, |v50|, v252
	v_max3_f32 v252, |v51|, |v52|, v252
	v_max_f32_e64 v252, |v53|, v252
	v_add_f32_e32 v62, v247, v254
	v_mov_b32_e32 v64, v252
	s_waitcnt vmcnt(15)
	v_lshlrev_b32_e32 v248, 16, v190
	v_and_b32_e32 v249, 0xffff0000, v190
	v_lshlrev_b32_e32 v250, 16, v191
	v_and_b32_e32 v251, 0xffff0000, v191
	v_pk_add_f32 v[46:47], v[46:47], v[248:249]
	v_pk_add_f32 v[48:49], v[48:49], v[250:251]
	v_lshlrev_b32_e32 v248, 16, v192
	v_and_b32_e32 v249, 0xffff0000, v192
	v_lshlrev_b32_e32 v250, 16, v193
	v_and_b32_e32 v251, 0xffff0000, v193
	v_pk_add_f32 v[42:43], v[42:43], v[248:249]
	v_pk_add_f32 v[44:45], v[44:45], v[250:251]
	v_cvt_pk_bf16_f32 v190, v46, v47
	v_cvt_pk_bf16_f32 v191, v48, v49
	v_cvt_pk_bf16_f32 v192, v42, v43
	v_cvt_pk_bf16_f32 v193, v44, v45
	v_add_u32_e32 v246, 0x129000, v245
	global_store_dwordx4 v246, v[190:193], s[100:101]
	v_mul_f32_e32 v247, v46, v46
	v_fmac_f32_e32 v247, v47, v47
	v_fmac_f32_e32 v247, v48, v48
	v_fmac_f32_e32 v247, v49, v49
	v_mul_f32_e32 v254, v42, v42
	v_fmac_f32_e32 v254, v43, v43
	v_fmac_f32_e32 v254, v44, v44
	v_fmac_f32_e32 v254, v45, v45
	v_max3_f32 v252, |v46|, |v47|, |v48|
	v_max3_f32 v252, |v49|, |v42|, v252
	v_max3_f32 v252, |v43|, |v44|, v252
	v_max_f32_e64 v252, |v45|, v252
	s_waitcnt vmcnt(15)
	v_lshlrev_b32_e32 v248, 16, v194
	v_and_b32_e32 v249, 0xffff0000, v194
	v_lshlrev_b32_e32 v250, 16, v195
	v_and_b32_e32 v251, 0xffff0000, v195
	v_pk_add_f32 v[38:39], v[38:39], v[248:249]
	v_pk_add_f32 v[40:41], v[40:41], v[250:251]
	v_lshlrev_b32_e32 v248, 16, v196
	v_and_b32_e32 v249, 0xffff0000, v196
	v_lshlrev_b32_e32 v250, 16, v197
	v_and_b32_e32 v251, 0xffff0000, v197
	v_pk_add_f32 v[34:35], v[34:35], v[248:249]
	v_pk_add_f32 v[36:37], v[36:37], v[250:251]
	v_cvt_pk_bf16_f32 v194, v38, v39
	v_cvt_pk_bf16_f32 v195, v40, v41
	v_cvt_pk_bf16_f32 v196, v34, v35
	v_cvt_pk_bf16_f32 v197, v36, v37
	v_add_u32_e32 v255, 0x129000, v245
	global_store_dwordx4 v255, v[194:197], s[100:101] offset:256
	v_fmac_f32_e32 v247, v38, v38
	v_fmac_f32_e32 v247, v39, v39
	v_fmac_f32_e32 v247, v40, v40
	v_fmac_f32_e32 v247, v41, v41
	v_fmac_f32_e32 v254, v34, v34
	v_fmac_f32_e32 v254, v35, v35
	v_fmac_f32_e32 v254, v36, v36
	v_fmac_f32_e32 v254, v37, v37
	v_max3_f32 v252, |v38|, |v39|, v252
	v_max_f32_e64 v252, |v40|, v252
	v_max3_f32 v252, |v41|, |v34|, v252
	v_max3_f32 v252, |v35|, |v36|, v252
	v_max_f32_e64 v252, |v37|, v252
	v_add_f32_e32 v46, v247, v254
	v_mov_b32_e32 v48, v252
	s_waitcnt vmcnt(15)
	v_lshlrev_b32_e32 v248, 16, v198
	v_and_b32_e32 v249, 0xffff0000, v198
	v_lshlrev_b32_e32 v250, 16, v199
	v_and_b32_e32 v251, 0xffff0000, v199
	v_pk_add_f32 v[30:31], v[30:31], v[248:249]
	v_pk_add_f32 v[32:33], v[32:33], v[250:251]
	v_lshlrev_b32_e32 v248, 16, v200
	v_and_b32_e32 v249, 0xffff0000, v200
	v_lshlrev_b32_e32 v250, 16, v201
	v_and_b32_e32 v251, 0xffff0000, v201
	v_pk_add_f32 v[26:27], v[26:27], v[248:249]
	v_pk_add_f32 v[28:29], v[28:29], v[250:251]
	v_cvt_pk_bf16_f32 v198, v30, v31
	v_cvt_pk_bf16_f32 v199, v32, v33
	v_cvt_pk_bf16_f32 v200, v26, v27
	v_cvt_pk_bf16_f32 v201, v28, v29
	v_add_u32_e32 v246, 0x14a000, v245
	global_store_dwordx4 v246, v[198:201], s[100:101]
	v_mul_f32_e32 v247, v30, v30
	v_fmac_f32_e32 v247, v31, v31
	v_fmac_f32_e32 v247, v32, v32
	v_fmac_f32_e32 v247, v33, v33
	v_mul_f32_e32 v254, v26, v26
	v_fmac_f32_e32 v254, v27, v27
	v_fmac_f32_e32 v254, v28, v28
	v_fmac_f32_e32 v254, v29, v29
	v_max3_f32 v252, |v30|, |v31|, |v32|
	v_max3_f32 v252, |v33|, |v26|, v252
	v_max3_f32 v252, |v27|, |v28|, v252
	v_max_f32_e64 v252, |v29|, v252
	s_waitcnt vmcnt(15)
	v_lshlrev_b32_e32 v248, 16, v202
	v_and_b32_e32 v249, 0xffff0000, v202
	v_lshlrev_b32_e32 v250, 16, v203
	v_and_b32_e32 v251, 0xffff0000, v203
	v_pk_add_f32 v[22:23], v[22:23], v[248:249]
	v_pk_add_f32 v[24:25], v[24:25], v[250:251]
	v_lshlrev_b32_e32 v248, 16, v204
	v_and_b32_e32 v249, 0xffff0000, v204
	v_lshlrev_b32_e32 v250, 16, v205
	v_and_b32_e32 v251, 0xffff0000, v205
	v_pk_add_f32 v[18:19], v[18:19], v[248:249]
	v_pk_add_f32 v[20:21], v[20:21], v[250:251]
	v_cvt_pk_bf16_f32 v202, v22, v23
	v_cvt_pk_bf16_f32 v203, v24, v25
	v_cvt_pk_bf16_f32 v204, v18, v19
	v_cvt_pk_bf16_f32 v205, v20, v21
	v_add_u32_e32 v255, 0x14a000, v245
	global_store_dwordx4 v255, v[202:205], s[100:101] offset:256
	v_fmac_f32_e32 v247, v22, v22
	v_fmac_f32_e32 v247, v23, v23
	v_fmac_f32_e32 v247, v24, v24
	v_fmac_f32_e32 v247, v25, v25
	v_fmac_f32_e32 v254, v18, v18
	v_fmac_f32_e32 v254, v19, v19
	v_fmac_f32_e32 v254, v20, v20
	v_fmac_f32_e32 v254, v21, v21
	v_max3_f32 v252, |v22|, |v23|, v252
	v_max_f32_e64 v252, |v24|, v252
	v_max3_f32 v252, |v25|, |v18|, v252
	v_max3_f32 v252, |v19|, |v20|, v252
	v_max_f32_e64 v252, |v21|, v252
	v_add_f32_e32 v30, v247, v254
	v_mov_b32_e32 v32, v252
	s_waitcnt vmcnt(15)
;     __device__ __forceinline__ void operator()(EPI_ARGS) const {
;     ...
;             for (int m = 0; m < 4; ++m) { const int row = row0 + ai * HALF + m * 16; const size_t off = (size_t)row * ldc + col0; float ss = 0.f, mx = 0.f;
; #pragma unroll
;                 for (int bj = 0; bj < 2; ++bj) {
;                     f32x4 a0, a1;
;                     if (RES_BF16) { const u32x4 rw = __builtin_bit_cast(u32x4, r0[m][bj]); a0 = (f32x4){bf_lo(rw.x), bf_hi(rw.x), bf_lo(rw.y), bf_hi(rw.y)}; a1 = (f32x4){bf_lo(rw.z), bf_hi(rw.z), bf_lo(rw.w), bf_hi(rw.w)};
;                         if (RES_SCALE) { const float rf = rfac[row]; a0 = a0 * rf; a1 = a1 * rf; } }
;                     else { a0 = r0[m][bj]; a1 = r1[m][bj]; }
;                     const f32x4 v0 = acc[ai][bj][m][0] + a0, v1 = acc[ai][bj][m][1] + a1;
;                     u32x4 w; w.x = cvt_pk_bf16(v0[0], v0[1]); w.y = cvt_pk_bf16(v0[2], v0[3]); w.z = cvt_pk_bf16(v1[0], v1[1]); w.w = cvt_pk_bf16(v1[2], v1[3]); *(u32x4*)(ob + off + bj * HALF) = w;
;                     ss += (v0[0] * v0[0] + v0[1] * v0[1]) + (v0[2] * v0[2] + v0[3] * v0[3]) + (v1[0] * v1[0] + v1[1] * v1[1]) + (v1[2] * v1[2] + v1[3] * v1[3]);
;                     if (rowmax) mx = fmaxf(mx, fmaxf(fmaxf(fmaxf(fabsf(v0[0]), fabsf(v0[1])), fmaxf(fabsf(v0[2]), fabsf(v0[3]))), fmaxf(fmaxf(fabsf(v1[0]), fabsf(v1[1])), fmaxf(fabsf(v1[2]), fabsf(v1[3]))))); }
;                 ss += __shfl_xor(ss, 16); ss += __shfl_xor(ss, 32); ssv[ai * 4 + m] = ss;
;                 if (rowmax) { mx = fmaxf(mx, __shfl_xor(mx, 16)); mx = fmaxf(mx, __shfl_xor(mx, 32)); } mxv[ai * 4 + m] = mx; }
;             asm volatile("" ::: "memory"); }
;         float s0 = 0.f, s1 = 0.f, m0 = 0.f, m1 = 0.f;
; #pragma unroll
;         for (int k = 0; k < 8; ++k) if ((k >> 1) == fq) { if (k & 1) { s1 = ssv[k]; m1 = mxv[k]; } else { s0 = ssv[k]; m0 = mxv[k]; } }
;         const int rq = row0 + (fq >> 1) * HALF + (fq & 1) * 32;
;         __hip_atomic_fetch_add(rowsq + rq, s0, __ATOMIC_RELAXED, __HIP_MEMORY_SCOPE_AGENT); __hip_atomic_fetch_add(rowsq + rq + 16, s1, __ATOMIC_RELAXED, __HIP_MEMORY_SCOPE_AGENT);
;         if (rowmax) { __hip_atomic_fetch_max(rowmax + rq, __float_as_uint(m0), __ATOMIC_RELAXED, __HIP_MEMORY_SCOPE_AGENT); __hip_atomic_fetch_max(rowmax + rq + 16, __float_as_uint(m1), __ATOMIC_RELAXED, __HIP_MEMORY_SCOPE_AGENT); }
	v_lshlrev_b32_e32 v248, 16, v206
	v_and_b32_e32 v249, 0xffff0000, v206
	v_lshlrev_b32_e32 v250, 16, v207
	v_and_b32_e32 v251, 0xffff0000, v207
	v_pk_add_f32 v[14:15], v[14:15], v[248:249]
	v_pk_add_f32 v[16:17], v[16:17], v[250:251]
	v_lshlrev_b32_e32 v248, 16, v208
	v_and_b32_e32 v249, 0xffff0000, v208
	v_lshlrev_b32_e32 v250, 16, v209
	v_and_b32_e32 v251, 0xffff0000, v209
	v_pk_add_f32 v[10:11], v[10:11], v[248:249]
	v_pk_add_f32 v[12:13], v[12:13], v[250:251]
	v_cvt_pk_bf16_f32 v206, v14, v15
	v_cvt_pk_bf16_f32 v207, v16, v17
	v_cvt_pk_bf16_f32 v208, v10, v11
	v_cvt_pk_bf16_f32 v209, v12, v13
	v_add_u32_e32 v246, 0x16b000, v245
	global_store_dwordx4 v246, v[206:209], s[100:101]
	v_mul_f32_e32 v247, v14, v14
	v_fmac_f32_e32 v247, v15, v15
	v_fmac_f32_e32 v247, v16, v16
	v_fmac_f32_e32 v247, v17, v17
	v_mul_f32_e32 v254, v10, v10
	v_fmac_f32_e32 v254, v11, v11
	v_fmac_f32_e32 v254, v12, v12
	v_fmac_f32_e32 v254, v13, v13
	v_max3_f32 v252, |v14|, |v15|, |v16|
	v_max3_f32 v252, |v17|, |v10|, v252
	v_max3_f32 v252, |v11|, |v12|, v252
	v_max_f32_e64 v252, |v13|, v252
	s_waitcnt vmcnt(15)
	v_lshlrev_b32_e32 v248, 16, v210
	v_and_b32_e32 v249, 0xffff0000, v210
	v_lshlrev_b32_e32 v250, 16, v211
	v_and_b32_e32 v251, 0xffff0000, v211
	v_pk_add_f32 v[6:7], v[6:7], v[248:249]
	v_pk_add_f32 v[8:9], v[8:9], v[250:251]
	v_lshlrev_b32_e32 v248, 16, v212
	v_and_b32_e32 v249, 0xffff0000, v212
	v_lshlrev_b32_e32 v250, 16, v213
	v_and_b32_e32 v251, 0xffff0000, v213
	v_pk_add_f32 v[2:3], v[2:3], v[248:249]
	v_pk_add_f32 v[4:5], v[4:5], v[250:251]
	v_cvt_pk_bf16_f32 v210, v6, v7
	v_cvt_pk_bf16_f32 v211, v8, v9
	v_cvt_pk_bf16_f32 v212, v2, v3
	v_cvt_pk_bf16_f32 v213, v4, v5
	v_add_u32_e32 v255, 0x16b000, v245
	global_store_dwordx4 v255, v[210:213], s[100:101] offset:256
	v_fmac_f32_e32 v247, v6, v6
	v_fmac_f32_e32 v247, v7, v7
	v_fmac_f32_e32 v247, v8, v8
	v_fmac_f32_e32 v247, v9, v9
	v_fmac_f32_e32 v254, v2, v2
	v_fmac_f32_e32 v254, v3, v3
	v_fmac_f32_e32 v254, v4, v4
	v_fmac_f32_e32 v254, v5, v5
	v_max3_f32 v252, |v6|, |v7|, v252
	v_max_f32_e64 v252, |v8|, v252
	v_max3_f32 v252, |v9|, |v2|, v252
	v_max3_f32 v252, |v3|, |v4|, v252
	v_max_f32_e64 v252, |v5|, v252
	v_add_f32_e32 v14, v247, v254
	v_mov_b32_e32 v16, v252
	v_and_b32_e32 v255, 63, v0
	v_xor_b32_e32 v252, 16, v255
	v_xor_b32_e32 v253, 32, v255
	v_lshlrev_b32_e32 v252, 2, v252
	v_lshlrev_b32_e32 v253, 2, v253
	ds_bpermute_b32 v127, v252, v126
	ds_bpermute_b32 v129, v252, v128
	ds_bpermute_b32 v111, v252, v110
	ds_bpermute_b32 v113, v252, v112
	ds_bpermute_b32 v95, v252, v94
	ds_bpermute_b32 v97, v252, v96
	ds_bpermute_b32 v79, v252, v78
	ds_bpermute_b32 v81, v252, v80
	ds_bpermute_b32 v63, v252, v62
	ds_bpermute_b32 v65, v252, v64
	ds_bpermute_b32 v47, v252, v46
	ds_bpermute_b32 v49, v252, v48
	ds_bpermute_b32 v31, v252, v30
	ds_bpermute_b32 v33, v252, v32
	ds_bpermute_b32 v15, v252, v14
	ds_bpermute_b32 v17, v252, v16
	s_waitcnt lgkmcnt(0)
	v_add_f32_e32 v126, v126, v127
	v_max_f32_e32 v128, v128, v129
	v_add_f32_e32 v110, v110, v111
	v_max_f32_e32 v112, v112, v113
	v_add_f32_e32 v94, v94, v95
	v_max_f32_e32 v96, v96, v97
	v_add_f32_e32 v78, v78, v79
	v_max_f32_e32 v80, v80, v81
	v_add_f32_e32 v62, v62, v63
	v_max_f32_e32 v64, v64, v65
	v_add_f32_e32 v46, v46, v47
	v_max_f32_e32 v48, v48, v49
	v_add_f32_e32 v30, v30, v31
	v_max_f32_e32 v32, v32, v33
	v_add_f32_e32 v14, v14, v15
	v_max_f32_e32 v16, v16, v17
	ds_bpermute_b32 v127, v253, v126
	ds_bpermute_b32 v129, v253, v128
	ds_bpermute_b32 v111, v253, v110
	ds_bpermute_b32 v113, v253, v112
	ds_bpermute_b32 v95, v253, v94
	ds_bpermute_b32 v97, v253, v96
	ds_bpermute_b32 v79, v253, v78
	ds_bpermute_b32 v81, v253, v80
	ds_bpermute_b32 v63, v253, v62
	ds_bpermute_b32 v65, v253, v64
	ds_bpermute_b32 v47, v253, v46
	ds_bpermute_b32 v49, v253, v48
	ds_bpermute_b32 v31, v253, v30
	ds_bpermute_b32 v33, v253, v32
	ds_bpermute_b32 v15, v253, v14
	ds_bpermute_b32 v17, v253, v16
	s_waitcnt lgkmcnt(0)
	v_add_f32_e32 v126, v126, v127
	v_max_f32_e32 v128, v128, v129
	v_add_f32_e32 v110, v110, v111
	v_max_f32_e32 v112, v112, v113
	v_add_f32_e32 v94, v94, v95
	v_max_f32_e32 v96, v96, v97
	v_add_f32_e32 v78, v78, v79
	v_max_f32_e32 v80, v80, v81
	v_add_f32_e32 v62, v62, v63
	v_max_f32_e32 v64, v64, v65
	v_add_f32_e32 v46, v46, v47
	v_max_f32_e32 v48, v48, v49
	v_add_f32_e32 v30, v30, v31
	v_max_f32_e32 v32, v32, v33
	v_add_f32_e32 v14, v14, v15
	v_max_f32_e32 v16, v16, v17
	v_cndmask_b32_e64 v248, 0, v126, s[2:3]
	v_cndmask_b32_e64 v249, 0, v110, s[2:3]
	v_cndmask_b32_e64 v248, v248, v94, s[4:5]
	v_cndmask_b32_e64 v249, v249, v78, s[4:5]
	v_cndmask_b32_e64 v248, v248, v62, s[6:7]
	v_cndmask_b32_e64 v249, v249, v46, s[6:7]
	v_cndmask_b32_e64 v248, v248, v30, s[8:9]
	v_cndmask_b32_e64 v249, v249, v14, s[8:9]
	v_lshl_add_u32 v250, s72, 8, v181
	v_add_u32_e32 v250, v180, v250
	v_lshlrev_b32_e32 v250, 2, v250
	global_atomic_add_f32 v250, v248, s[54:55]
	global_atomic_add_f32 v250, v249, s[54:55] offset:64
	v_cndmask_b32_e64 v247, 0, v128, s[2:3]
	v_cndmask_b32_e64 v254, 0, v112, s[2:3]
	v_cndmask_b32_e64 v247, v247, v96, s[4:5]
	v_cndmask_b32_e64 v254, v254, v80, s[4:5]
	v_cndmask_b32_e64 v247, v247, v64, s[6:7]
	v_cndmask_b32_e64 v254, v254, v48, s[6:7]
	v_cndmask_b32_e64 v247, v247, v32, s[8:9]
	v_cndmask_b32_e64 v254, v254, v16, s[8:9]
	global_atomic_umax v250, v247, s[56:57]
	global_atomic_umax v250, v254, s[56:57] offset:64
	s_and_b64 vcc, exec, s[10:11]
	s_mov_b64 s[10:11], -1
	s_cbranch_vccnz .LBB0_992
	s_andn2_b64 vcc, exec, s[0:1]
	s_cbranch_vccnz .LBB0_991
	s_barrier
	s_branch .LBB0_991

; #define GAS __attribute__((address_space(1)))
; __device__ __forceinline__ float bf_lo(unsigned w) { return __uint_as_float(w << 16); }
; __device__ __forceinline__ float bf_hi(unsigned w) { return __uint_as_float(w & 0xffff0000u); }
; __device__ __forceinline__ unsigned pack4_i8(int a, int b, int c, int d) { return (unsigned)(a & 0xff) | ((unsigned)(b & 0xff) << 8) | ((unsigned)(c & 0xff) << 16) | ((unsigned)d << 24); }
; __device__ __forceinline__ int quant_i8(float x, float inv) { return (int)fminf(fmaxf(__builtin_rintf(x * inv), -127.0f), 127.0f); }
; __device__ __forceinline__ void quant_row_i8(const bf16* hrow, unsigned char* qrow, float amax, int lane) {
;     const float inv = amax > 0.f ? 127.0f / amax : 0.f;
; #pragma unroll
;     for (int it = 0; it < 4; ++it) { const GAS u32x4* src = (const GAS u32x4*)(hrow + it * 1024 + lane * 16); const u32x4 a = src[0], b = src[1];
;         u32x4 o;
;         o.x = pack4_i8(quant_i8(bf_lo(a.x), inv), quant_i8(bf_hi(a.x), inv), quant_i8(bf_lo(a.y), inv), quant_i8(bf_hi(a.y), inv));
;         o.y = pack4_i8(quant_i8(bf_lo(a.z), inv), quant_i8(bf_hi(a.z), inv), quant_i8(bf_lo(a.w), inv), quant_i8(bf_hi(a.w), inv));
;         o.z = pack4_i8(quant_i8(bf_lo(b.x), inv), quant_i8(bf_hi(b.x), inv), quant_i8(bf_lo(b.y), inv), quant_i8(bf_hi(b.y), inv));
;         o.w = pack4_i8(quant_i8(bf_lo(b.z), inv), quant_i8(bf_hi(b.z), inv), quant_i8(bf_lo(b.w), inv), quant_i8(bf_hi(b.w), inv));
;         *(GAS u32x4*)(qrow + it * 1024 + lane * 16) = o; }
; __global__ void __launch_bounds__(NWAVES * 64, 2) fwd_kernel(Args args) {
;     ...
;         for (int m = gw; m < MTOK; m += NGW) quant_row_i8(HB + (size_t)m * DM, A8 + (size_t)m * DM, __uint_as_float(__hip_atomic_load(rmaxU + m, __ATOMIC_RELAXED, __HIP_MEMORY_SCOPE_AGENT)), lane);
.LBB0_1120:
	s_or_b64 exec, exec, s[0:1]
	v_readlane_b32 s36, v244, 2
	s_cmpk_gt_i32 s18, 0x3fff
	v_readlane_b32 s50, v244, 16
	v_readlane_b32 s51, v244, 17
	s_waitcnt lgkmcnt(0)
	s_barrier
	v_readlane_b32 s37, v244, 3
	v_readlane_b32 s38, v244, 4
	v_readlane_b32 s39, v244, 5
	v_readlane_b32 s40, v244, 6
	v_readlane_b32 s41, v244, 7
	v_readlane_b32 s42, v244, 8
	v_readlane_b32 s43, v244, 9
	v_readlane_b32 s44, v244, 10
	v_readlane_b32 s45, v244, 11
	v_readlane_b32 s46, v244, 12
	v_readlane_b32 s47, v244, 13
	v_readlane_b32 s48, v244, 14
	v_readlane_b32 s49, v244, 15
	s_cbranch_scc1 .LBB0_1123
	s_ashr_i32 s19, s18, 31
	s_lshl_b64 s[0:1], s[18:19], 2
	s_add_u32 s14, s0, 0x85800
	v_and_b32_e32 v1, 0x3f0, v1
	s_addc_u32 s15, s1, 0
	s_lshl_b64 s[2:3], s[18:19], 12
	s_ashr_i32 s21, s20, 31
	s_waitcnt vmcnt(47)
	v_or_b32_e32 v2, s2, v1
	s_mul_i32 s4, s18, 0x2100
	s_mov_b32 s5, 0
	v_and_b32_e32 v1, 63, v0
	s_lshl_b64 s[0:1], s[20:21], 2
	v_mov_b32_e32 v3, s3
	s_lshl_b64 s[2:3], s[20:21], 12
	v_lshl_add_u32 v4, v1, 5, s4
	v_mov_b32_e32 v5, s5
	s_mul_i32 s4, s20, 0x2100
	s_mov_b32 s5, 0
	v_mov_b32_e32 v1, 0
	s_mov_b32 s17, 0x42fe0000
	s_mov_b64 s[6:7], 0
	s_mov_b32 s19, 0
	s_mov_b32 s21, 0xc2fe0000
	s_waitcnt vmcnt(45)
	v_mov_b32_e32 v12, 0x42fe0000
	s_mov_b32 s23, 0x40c0c00
	s_mov_b32 s24, 0x1c700000
	s_mov_b64 s[8:9], 0x800
	s_mov_b64 s[10:11], 0x1000
	s_mov_b32 s25, 0x1000
	s_mov_b64 s[12:13], 0x1800
	s_mov_b32 s26, s18

; __device__ __forceinline__ unsigned cvt_pk_bf16(float lo, float hi) { unsigned r; asm volatile("v_cvt_pk_bf16_f32 %0, %1, %2" : "=v"(r) : "v"(lo), "v"(hi)); return r; }
; __device__ __forceinline__ float bf_lo(unsigned w) { return __uint_as_float(w << 16); }
; __device__ __forceinline__ float bf_hi(unsigned w) { return __uint_as_float(w & 0xffff0000u); }
;     __device__ __forceinline__ void operator()(EPI_ARGS) const {
;     ...
;                 for (int bj = 0; bj < 2; ++bj) { const size_t off = (size_t)(row0 + ai * HALF + m * 16) * ldc + col0 + bj * HALF;
;                     if (RES_BF16) { const u32x4 rw = *(const u32x4*)((const bf16*)resid + off); r0[m][bj] = __builtin_bit_cast(f32x4, rw); }
;                     else { r0[m][bj] = *(const f32x4*)((const float*)resid + off); r1[m][bj] = *(const f32x4*)((const float*)resid + off + 4); } }
; #pragma unroll
;             for (int m = 0; m < 4; ++m) { const int row = row0 + ai * HALF + m * 16; const size_t off = (size_t)row * ldc + col0; float ss = 0.f, mx = 0.f;
; #pragma unroll
;                 for (int bj = 0; bj < 2; ++bj) {
;                     f32x4 a0, a1;
;                     if (RES_BF16) { const u32x4 rw = __builtin_bit_cast(u32x4, r0[m][bj]); a0 = (f32x4){bf_lo(rw.x), bf_hi(rw.x), bf_lo(rw.y), bf_hi(rw.y)}; a1 = (f32x4){bf_lo(rw.z), bf_hi(rw.z), bf_lo(rw.w), bf_hi(rw.w)};
;                         if (RES_SCALE) { const float rf = rfac[row]; a0 = a0 * rf; a1 = a1 * rf; } }
;                     else { a0 = r0[m][bj]; a1 = r1[m][bj]; }
;                     const f32x4 v0 = acc[ai][bj][m][0] + a0, v1 = acc[ai][bj][m][1] + a1;
;                     u32x4 w; w.x = cvt_pk_bf16(v0[0], v0[1]); w.y = cvt_pk_bf16(v0[2], v0[3]); w.z = cvt_pk_bf16(v1[0], v1[1]); w.w = cvt_pk_bf16(v1[2], v1[3]); *(u32x4*)(ob + off + bj * HALF) = w;
;                     ss += (v0[0] * v0[0] + v0[1] * v0[1]) + (v0[2] * v0[2] + v0[3] * v0[3]) + (v1[0] * v1[0] + v1[1] * v1[1]) + (v1[2] * v1[2] + v1[3] * v1[3]);
.LBB0_1364:
	s_nop 7
	v_lshl_add_u32 v245, s72, 8, v157
	v_mul_u32_u24_e32 v245, 0x2100, v245
	v_lshl_or_b32 v246, s73, 8, v159
	v_lshl_add_u32 v245, v246, 1, v245
	global_load_dwordx4 v[130:133], v245, s[100:101]
	global_load_dwordx4 v[134:137], v245, s[100:101] offset:256
	v_add_u32_e32 v246, 0x21000, v245
	global_load_dwordx4 v[142:145], v246, s[100:101]
	global_load_dwordx4 v[146:149], v246, s[100:101] offset:256
	v_add_u32_e32 v255, 0x42000, v245
	global_load_dwordx4 v[150:153], v255, s[100:101]
	global_load_dwordx4 v[166:169], v255, s[100:101] offset:256
	v_add_u32_e32 v246, 0x63000, v245
	global_load_dwordx4 v[170:173], v246, s[100:101]
	global_load_dwordx4 v[174:177], v246, s[100:101] offset:256
	v_add_u32_e32 v255, 0x108000, v245
	global_load_dwordx4 v[178:181], v255, s[100:101]
	global_load_dwordx4 v[182:185], v255, s[100:101] offset:256
	v_add_u32_e32 v246, 0x129000, v245
	global_load_dwordx4 v[186:189], v246, s[100:101]
	global_load_dwordx4 v[190:193], v246, s[100:101] offset:256
	v_add_u32_e32 v255, 0x14a000, v245
	global_load_dwordx4 v[194:197], v255, s[100:101]
	global_load_dwordx4 v[198:201], v255, s[100:101] offset:256
	v_add_u32_e32 v246, 0x16b000, v245
	global_load_dwordx4 v[202:205], v246, s[100:101]
	global_load_dwordx4 v[206:209], v246, s[100:101] offset:256
	s_waitcnt vmcnt(15)
	v_lshlrev_b32_e32 v248, 16, v130
	v_and_b32_e32 v249, 0xffff0000, v130
	v_lshlrev_b32_e32 v250, 16, v131
	v_and_b32_e32 v251, 0xffff0000, v131
	v_pk_add_f32 v[126:127], v[126:127], v[248:249]
	v_pk_add_f32 v[128:129], v[128:129], v[250:251]
	v_lshlrev_b32_e32 v248, 16, v132
	v_and_b32_e32 v249, 0xffff0000, v132
	v_lshlrev_b32_e32 v250, 16, v133
	v_and_b32_e32 v251, 0xffff0000, v133
	v_pk_add_f32 v[122:123], v[122:123], v[248:249]
	v_pk_add_f32 v[124:125], v[124:125], v[250:251]
	v_cvt_pk_bf16_f32 v130, v126, v127
	v_cvt_pk_bf16_f32 v131, v128, v129
	v_cvt_pk_bf16_f32 v132, v122, v123
	v_cvt_pk_bf16_f32 v133, v124, v125
	global_store_dwordx4 v245, v[130:133], s[98:99]
	v_mul_f32_e32 v247, v126, v126
	v_fmac_f32_e32 v247, v127, v127
	v_fmac_f32_e32 v247, v128, v128
	v_fmac_f32_e32 v247, v129, v129
	v_mul_f32_e32 v254, v122, v122
	v_fmac_f32_e32 v254, v123, v123
	v_fmac_f32_e32 v254, v124, v124
	v_fmac_f32_e32 v254, v125, v125
	s_waitcnt vmcnt(15)
	v_lshlrev_b32_e32 v248, 16, v134
	v_and_b32_e32 v249, 0xffff0000, v134
	v_lshlrev_b32_e32 v250, 16, v135
	v_and_b32_e32 v251, 0xffff0000, v135
	v_pk_add_f32 v[118:119], v[118:119], v[248:249]
	v_pk_add_f32 v[120:121], v[120:121], v[250:251]
	v_lshlrev_b32_e32 v248, 16, v136
	v_and_b32_e32 v249, 0xffff0000, v136
	v_lshlrev_b32_e32 v250, 16, v137
	v_and_b32_e32 v251, 0xffff0000, v137
	v_pk_add_f32 v[114:115], v[114:115], v[248:249]
	v_pk_add_f32 v[116:117], v[116:117], v[250:251]
	v_cvt_pk_bf16_f32 v134, v118, v119
	v_cvt_pk_bf16_f32 v135, v120, v121
	v_cvt_pk_bf16_f32 v136, v114, v115
	v_cvt_pk_bf16_f32 v137, v116, v117
	global_store_dwordx4 v245, v[134:137], s[98:99] offset:256
	v_fmac_f32_e32 v247, v118, v118
	v_fmac_f32_e32 v247, v119, v119
	v_fmac_f32_e32 v247, v120, v120
	v_fmac_f32_e32 v247, v121, v121
	v_fmac_f32_e32 v254, v114, v114
	v_fmac_f32_e32 v254, v115, v115
	v_fmac_f32_e32 v254, v116, v116
	v_fmac_f32_e32 v254, v117, v117
	v_add_f32_e32 v126, v247, v254
	s_waitcnt vmcnt(15)
	v_lshlrev_b32_e32 v248, 16, v142
	v_and_b32_e32 v249, 0xffff0000, v142
	v_lshlrev_b32_e32 v250, 16, v143
	v_and_b32_e32 v251, 0xffff0000, v143
	v_pk_add_f32 v[110:111], v[110:111], v[248:249]
	v_pk_add_f32 v[112:113], v[112:113], v[250:251]
	v_lshlrev_b32_e32 v248, 16, v144
	v_and_b32_e32 v249, 0xffff0000, v144
	v_lshlrev_b32_e32 v250, 16, v145
	v_and_b32_e32 v251, 0xffff0000, v145
	v_pk_add_f32 v[106:107], v[106:107], v[248:249]
	v_pk_add_f32 v[108:109], v[108:109], v[250:251]
	v_cvt_pk_bf16_f32 v142, v110, v111
	v_cvt_pk_bf16_f32 v143, v112, v113
	v_cvt_pk_bf16_f32 v144, v106, v107
	v_cvt_pk_bf16_f32 v145, v108, v109
	v_add_u32_e32 v246, 0x21000, v245
	global_store_dwordx4 v246, v[142:145], s[98:99]
	v_mul_f32_e32 v247, v110, v110
	v_fmac_f32_e32 v247, v111, v111
	v_fmac_f32_e32 v247, v112, v112
	v_fmac_f32_e32 v247, v113, v113
	v_mul_f32_e32 v254, v106, v106
	v_fmac_f32_e32 v254, v107, v107
	v_fmac_f32_e32 v254, v108, v108
	v_fmac_f32_e32 v254, v109, v109
	s_waitcnt vmcnt(15)
	v_lshlrev_b32_e32 v248, 16, v146
	v_and_b32_e32 v249, 0xffff0000, v146
	v_lshlrev_b32_e32 v250, 16, v147
	v_and_b32_e32 v251, 0xffff0000, v147
	v_pk_add_f32 v[102:103], v[102:103], v[248:249]
	v_pk_add_f32 v[104:105], v[104:105], v[250:251]
	v_lshlrev_b32_e32 v248, 16, v148
	v_and_b32_e32 v249, 0xffff0000, v148
	v_lshlrev_b32_e32 v250, 16, v149
	v_and_b32_e32 v251, 0xffff0000, v149
	v_pk_add_f32 v[98:99], v[98:99], v[248:249]
	v_pk_add_f32 v[100:101], v[100:101], v[250:251]
	v_cvt_pk_bf16_f32 v146, v102, v103
	v_cvt_pk_bf16_f32 v147, v104, v105
	v_cvt_pk_bf16_f32 v148, v98, v99
	v_cvt_pk_bf16_f32 v149, v100, v101
	v_add_u32_e32 v255, 0x21000, v245
	global_store_dwordx4 v255, v[146:149], s[98:99] offset:256
	v_fmac_f32_e32 v247, v102, v102
	v_fmac_f32_e32 v247, v103, v103
	v_fmac_f32_e32 v247, v104, v104
	v_fmac_f32_e32 v247, v105, v105
	v_fmac_f32_e32 v254, v98, v98
	v_fmac_f32_e32 v254, v99, v99
	v_fmac_f32_e32 v254, v100, v100
	v_fmac_f32_e32 v254, v101, v101
	v_add_f32_e32 v110, v247, v254
	s_waitcnt vmcnt(15)
; __device__ __forceinline__ unsigned cvt_pk_bf16(float lo, float hi) { unsigned r; asm volatile("v_cvt_pk_bf16_f32 %0, %1, %2" : "=v"(r) : "v"(lo), "v"(hi)); return r; }
; __device__ __forceinline__ float bf_lo(unsigned w) { return __uint_as_float(w << 16); }
; __device__ __forceinline__ float bf_hi(unsigned w) { return __uint_as_float(w & 0xffff0000u); }
;     __device__ __forceinline__ void operator()(EPI_ARGS) const {
;     ...
;             for (int m = 0; m < 4; ++m) { const int row = row0 + ai * HALF + m * 16; const size_t off = (size_t)row * ldc + col0; float ss = 0.f, mx = 0.f;
; #pragma unroll
;                 for (int bj = 0; bj < 2; ++bj) {
;                     f32x4 a0, a1;
;                     if (RES_BF16) { const u32x4 rw = __builtin_bit_cast(u32x4, r0[m][bj]); a0 = (f32x4){bf_lo(rw.x), bf_hi(rw.x), bf_lo(rw.y), bf_hi(rw.y)}; a1 = (f32x4){bf_lo(rw.z), bf_hi(rw.z), bf_lo(rw.w), bf_hi(rw.w)};
;                         if (RES_SCALE) { const float rf = rfac[row]; a0 = a0 * rf; a1 = a1 * rf; } }
;                     else { a0 = r0[m][bj]; a1 = r1[m][bj]; }
;                     const f32x4 v0 = acc[ai][bj][m][0] + a0, v1 = acc[ai][bj][m][1] + a1;
;                     u32x4 w; w.x = cvt_pk_bf16(v0[0], v0[1]); w.y = cvt_pk_bf16(v0[2], v0[3]); w.z = cvt_pk_bf16(v1[0], v1[1]); w.w = cvt_pk_bf16(v1[2], v1[3]); *(u32x4*)(ob + off + bj * HALF) = w;
;                     ss += (v0[0] * v0[0] + v0[1] * v0[1]) + (v0[2] * v0[2] + v0[3] * v0[3]) + (v1[0] * v1[0] + v1[1] * v1[1]) + (v1[2] * v1[2] + v1[3] * v1[3]);
;                     if (rowmax) mx = fmaxf(mx, fmaxf(fmaxf(fmaxf(fabsf(v0[0]), fabsf(v0[1])), fmaxf(fabsf(v0[2]), fabsf(v0[3]))), fmaxf(fmaxf(fabsf(v1[0]), fabsf(v1[1])), fmaxf(fabsf(v1[2]), fabsf(v1[3]))))); }
;                 ss += __shfl_xor(ss, 16); ss += __shfl_xor(ss, 32); ssv[ai * 4 + m] = ss;
	v_lshlrev_b32_e32 v248, 16, v150
	v_and_b32_e32 v249, 0xffff0000, v150
	v_lshlrev_b32_e32 v250, 16, v151
	v_and_b32_e32 v251, 0xffff0000, v151
	v_pk_add_f32 v[94:95], v[94:95], v[248:249]
	v_pk_add_f32 v[96:97], v[96:97], v[250:251]
	v_lshlrev_b32_e32 v248, 16, v152
	v_and_b32_e32 v249, 0xffff0000, v152
	v_lshlrev_b32_e32 v250, 16, v153
	v_and_b32_e32 v251, 0xffff0000, v153
	v_pk_add_f32 v[90:91], v[90:91], v[248:249]
	v_pk_add_f32 v[92:93], v[92:93], v[250:251]
	v_cvt_pk_bf16_f32 v150, v94, v95
	v_cvt_pk_bf16_f32 v151, v96, v97
	v_cvt_pk_bf16_f32 v152, v90, v91
	v_cvt_pk_bf16_f32 v153, v92, v93
	v_add_u32_e32 v246, 0x42000, v245
	global_store_dwordx4 v246, v[150:153], s[98:99]
	v_mul_f32_e32 v247, v94, v94
	v_fmac_f32_e32 v247, v95, v95
	v_fmac_f32_e32 v247, v96, v96
	v_fmac_f32_e32 v247, v97, v97
	v_mul_f32_e32 v254, v90, v90
	v_fmac_f32_e32 v254, v91, v91
	v_fmac_f32_e32 v254, v92, v92
	v_fmac_f32_e32 v254, v93, v93
	s_waitcnt vmcnt(15)
	v_lshlrev_b32_e32 v248, 16, v166
	v_and_b32_e32 v249, 0xffff0000, v166
	v_lshlrev_b32_e32 v250, 16, v167
	v_and_b32_e32 v251, 0xffff0000, v167
	v_pk_add_f32 v[86:87], v[86:87], v[248:249]
	v_pk_add_f32 v[88:89], v[88:89], v[250:251]
	v_lshlrev_b32_e32 v248, 16, v168
	v_and_b32_e32 v249, 0xffff0000, v168
	v_lshlrev_b32_e32 v250, 16, v169
	v_and_b32_e32 v251, 0xffff0000, v169
	v_pk_add_f32 v[82:83], v[82:83], v[248:249]
	v_pk_add_f32 v[84:85], v[84:85], v[250:251]
	v_cvt_pk_bf16_f32 v166, v86, v87
	v_cvt_pk_bf16_f32 v167, v88, v89
	v_cvt_pk_bf16_f32 v168, v82, v83
	v_cvt_pk_bf16_f32 v169, v84, v85
	v_add_u32_e32 v255, 0x42000, v245
	global_store_dwordx4 v255, v[166:169], s[98:99] offset:256
	v_fmac_f32_e32 v247, v86, v86
	v_fmac_f32_e32 v247, v87, v87
	v_fmac_f32_e32 v247, v88, v88
	v_fmac_f32_e32 v247, v89, v89
	v_fmac_f32_e32 v254, v82, v82
	v_fmac_f32_e32 v254, v83, v83
	v_fmac_f32_e32 v254, v84, v84
	v_fmac_f32_e32 v254, v85, v85
	v_add_f32_e32 v94, v247, v254
	s_waitcnt vmcnt(15)
	v_lshlrev_b32_e32 v248, 16, v170
	v_and_b32_e32 v249, 0xffff0000, v170
	v_lshlrev_b32_e32 v250, 16, v171
	v_and_b32_e32 v251, 0xffff0000, v171
	v_pk_add_f32 v[78:79], v[78:79], v[248:249]
	v_pk_add_f32 v[80:81], v[80:81], v[250:251]
	v_lshlrev_b32_e32 v248, 16, v172
	v_and_b32_e32 v249, 0xffff0000, v172
	v_lshlrev_b32_e32 v250, 16, v173
	v_and_b32_e32 v251, 0xffff0000, v173
	v_pk_add_f32 v[74:75], v[74:75], v[248:249]
	v_pk_add_f32 v[76:77], v[76:77], v[250:251]
	v_cvt_pk_bf16_f32 v170, v78, v79
	v_cvt_pk_bf16_f32 v171, v80, v81
	v_cvt_pk_bf16_f32 v172, v74, v75
	v_cvt_pk_bf16_f32 v173, v76, v77
	v_add_u32_e32 v246, 0x63000, v245
	global_store_dwordx4 v246, v[170:173], s[98:99]
	v_mul_f32_e32 v247, v78, v78
	v_fmac_f32_e32 v247, v79, v79
	v_fmac_f32_e32 v247, v80, v80
	v_fmac_f32_e32 v247, v81, v81
	v_mul_f32_e32 v254, v74, v74
	v_fmac_f32_e32 v254, v75, v75
	v_fmac_f32_e32 v254, v76, v76
	v_fmac_f32_e32 v254, v77, v77
	s_waitcnt vmcnt(15)
	v_lshlrev_b32_e32 v248, 16, v174
	v_and_b32_e32 v249, 0xffff0000, v174
	v_lshlrev_b32_e32 v250, 16, v175
	v_and_b32_e32 v251, 0xffff0000, v175
	v_pk_add_f32 v[70:71], v[70:71], v[248:249]
	v_pk_add_f32 v[72:73], v[72:73], v[250:251]
	v_lshlrev_b32_e32 v248, 16, v176
	v_and_b32_e32 v249, 0xffff0000, v176
	v_lshlrev_b32_e32 v250, 16, v177
	v_and_b32_e32 v251, 0xffff0000, v177
	v_pk_add_f32 v[66:67], v[66:67], v[248:249]
	v_pk_add_f32 v[68:69], v[68:69], v[250:251]
	v_cvt_pk_bf16_f32 v174, v70, v71
	v_cvt_pk_bf16_f32 v175, v72, v73
	v_cvt_pk_bf16_f32 v176, v66, v67
	v_cvt_pk_bf16_f32 v177, v68, v69
	v_add_u32_e32 v255, 0x63000, v245
	global_store_dwordx4 v255, v[174:177], s[98:99] offset:256
	v_fmac_f32_e32 v247, v70, v70
	v_fmac_f32_e32 v247, v71, v71
	v_fmac_f32_e32 v247, v72, v72
	v_fmac_f32_e32 v247, v73, v73
	v_fmac_f32_e32 v254, v66, v66
	v_fmac_f32_e32 v254, v67, v67
	v_fmac_f32_e32 v254, v68, v68
	v_fmac_f32_e32 v254, v69, v69
	v_add_f32_e32 v78, v247, v254
	s_waitcnt vmcnt(15)
	v_lshlrev_b32_e32 v248, 16, v178
	v_and_b32_e32 v249, 0xffff0000, v178
	v_lshlrev_b32_e32 v250, 16, v179
	v_and_b32_e32 v251, 0xffff0000, v179
	v_pk_add_f32 v[62:63], v[62:63], v[248:249]
	v_pk_add_f32 v[64:65], v[64:65], v[250:251]
	v_lshlrev_b32_e32 v248, 16, v180
	v_and_b32_e32 v249, 0xffff0000, v180
	v_lshlrev_b32_e32 v250, 16, v181
	v_and_b32_e32 v251, 0xffff0000, v181
	v_pk_add_f32 v[58:59], v[58:59], v[248:249]
	v_pk_add_f32 v[60:61], v[60:61], v[250:251]
	v_cvt_pk_bf16_f32 v178, v62, v63
	v_cvt_pk_bf16_f32 v179, v64, v65
	v_cvt_pk_bf16_f32 v180, v58, v59
	v_cvt_pk_bf16_f32 v181, v60, v61
	v_add_u32_e32 v246, 0x108000, v245
	global_store_dwordx4 v246, v[178:181], s[98:99]
	v_mul_f32_e32 v247, v62, v62
	v_fmac_f32_e32 v247, v63, v63
	v_fmac_f32_e32 v247, v64, v64
	v_fmac_f32_e32 v247, v65, v65
	v_mul_f32_e32 v254, v58, v58
	v_fmac_f32_e32 v254, v59, v59
	v_fmac_f32_e32 v254, v60, v60
	v_fmac_f32_e32 v254, v61, v61
	s_waitcnt vmcnt(15)
	v_lshlrev_b32_e32 v248, 16, v182
	v_and_b32_e32 v249, 0xffff0000, v182
	v_lshlrev_b32_e32 v250, 16, v183
	v_and_b32_e32 v251, 0xffff0000, v183
	v_pk_add_f32 v[54:55], v[54:55], v[248:249]
	v_pk_add_f32 v[56:57], v[56:57], v[250:251]
	v_lshlrev_b32_e32 v248, 16, v184
	v_and_b32_e32 v249, 0xffff0000, v184
	v_lshlrev_b32_e32 v250, 16, v185
	v_and_b32_e32 v251, 0xffff0000, v185
	v_pk_add_f32 v[50:51], v[50:51], v[248:249]
	v_pk_add_f32 v[52:53], v[52:53], v[250:251]
	v_cvt_pk_bf16_f32 v182, v54, v55
	v_cvt_pk_bf16_f32 v183, v56, v57
	v_cvt_pk_bf16_f32 v184, v50, v51
	v_cvt_pk_bf16_f32 v185, v52, v53
	v_add_u32_e32 v255, 0x108000, v245
	global_store_dwordx4 v255, v[182:185], s[98:99] offset:256
	v_fmac_f32_e32 v247, v54, v54
	v_fmac_f32_e32 v247, v55, v55
	v_fmac_f32_e32 v247, v56, v56
	v_fmac_f32_e32 v247, v57, v57
	v_fmac_f32_e32 v254, v50, v50
	v_fmac_f32_e32 v254, v51, v51
	v_fmac_f32_e32 v254, v52, v52
	v_fmac_f32_e32 v254, v53, v53
	v_add_f32_e32 v62, v247, v254
	s_waitcnt vmcnt(15)
; __device__ __forceinline__ unsigned cvt_pk_bf16(float lo, float hi) { unsigned r; asm volatile("v_cvt_pk_bf16_f32 %0, %1, %2" : "=v"(r) : "v"(lo), "v"(hi)); return r; }
; __device__ __forceinline__ float bf_lo(unsigned w) { return __uint_as_float(w << 16); }
; __device__ __forceinline__ float bf_hi(unsigned w) { return __uint_as_float(w & 0xffff0000u); }
;     __device__ __forceinline__ void operator()(EPI_ARGS) const {
;     ...
;             for (int m = 0; m < 4; ++m) { const int row = row0 + ai * HALF + m * 16; const size_t off = (size_t)row * ldc + col0; float ss = 0.f, mx = 0.f;
; #pragma unroll
;                 for (int bj = 0; bj < 2; ++bj) {
;                     f32x4 a0, a1;
;                     if (RES_BF16) { const u32x4 rw = __builtin_bit_cast(u32x4, r0[m][bj]); a0 = (f32x4){bf_lo(rw.x), bf_hi(rw.x), bf_lo(rw.y), bf_hi(rw.y)}; a1 = (f32x4){bf_lo(rw.z), bf_hi(rw.z), bf_lo(rw.w), bf_hi(rw.w)};
;                         if (RES_SCALE) { const float rf = rfac[row]; a0 = a0 * rf; a1 = a1 * rf; } }
;                     else { a0 = r0[m][bj]; a1 = r1[m][bj]; }
;                     const f32x4 v0 = acc[ai][bj][m][0] + a0, v1 = acc[ai][bj][m][1] + a1;
;                     u32x4 w; w.x = cvt_pk_bf16(v0[0], v0[1]); w.y = cvt_pk_bf16(v0[2], v0[3]); w.z = cvt_pk_bf16(v1[0], v1[1]); w.w = cvt_pk_bf16(v1[2], v1[3]); *(u32x4*)(ob + off + bj * HALF) = w;
;                     ss += (v0[0] * v0[0] + v0[1] * v0[1]) + (v0[2] * v0[2] + v0[3] * v0[3]) + (v1[0] * v1[0] + v1[1] * v1[1]) + (v1[2] * v1[2] + v1[3] * v1[3]);
;                     if (rowmax) mx = fmaxf(mx, fmaxf(fmaxf(fmaxf(fabsf(v0[0]), fabsf(v0[1])), fmaxf(fabsf(v0[2]), fabsf(v0[3]))), fmaxf(fmaxf(fabsf(v1[0]), fabsf(v1[1])), fmaxf(fabsf(v1[2]), fabsf(v1[3]))))); }
;                 ss += __shfl_xor(ss, 16); ss += __shfl_xor(ss, 32); ssv[ai * 4 + m] = ss;
	v_lshlrev_b32_e32 v248, 16, v186
	v_and_b32_e32 v249, 0xffff0000, v186
	v_lshlrev_b32_e32 v250, 16, v187
	v_and_b32_e32 v251, 0xffff0000, v187
	v_pk_add_f32 v[46:47], v[46:47], v[248:249]
	v_pk_add_f32 v[48:49], v[48:49], v[250:251]
	v_lshlrev_b32_e32 v248, 16, v188
	v_and_b32_e32 v249, 0xffff0000, v188
	v_lshlrev_b32_e32 v250, 16, v189
	v_and_b32_e32 v251, 0xffff0000, v189
	v_pk_add_f32 v[42:43], v[42:43], v[248:249]
	v_pk_add_f32 v[44:45], v[44:45], v[250:251]
	v_cvt_pk_bf16_f32 v186, v46, v47
	v_cvt_pk_bf16_f32 v187, v48, v49
	v_cvt_pk_bf16_f32 v188, v42, v43
	v_cvt_pk_bf16_f32 v189, v44, v45
	v_add_u32_e32 v246, 0x129000, v245
	global_store_dwordx4 v246, v[186:189], s[98:99]
	v_mul_f32_e32 v247, v46, v46
	v_fmac_f32_e32 v247, v47, v47
	v_fmac_f32_e32 v247, v48, v48
	v_fmac_f32_e32 v247, v49, v49
	v_mul_f32_e32 v254, v42, v42
	v_fmac_f32_e32 v254, v43, v43
	v_fmac_f32_e32 v254, v44, v44
	v_fmac_f32_e32 v254, v45, v45
	s_waitcnt vmcnt(15)
	v_lshlrev_b32_e32 v248, 16, v190
	v_and_b32_e32 v249, 0xffff0000, v190
	v_lshlrev_b32_e32 v250, 16, v191
	v_and_b32_e32 v251, 0xffff0000, v191
	v_pk_add_f32 v[38:39], v[38:39], v[248:249]
	v_pk_add_f32 v[40:41], v[40:41], v[250:251]
	v_lshlrev_b32_e32 v248, 16, v192
	v_and_b32_e32 v249, 0xffff0000, v192
	v_lshlrev_b32_e32 v250, 16, v193
	v_and_b32_e32 v251, 0xffff0000, v193
	v_pk_add_f32 v[34:35], v[34:35], v[248:249]
	v_pk_add_f32 v[36:37], v[36:37], v[250:251]
	v_cvt_pk_bf16_f32 v190, v38, v39
	v_cvt_pk_bf16_f32 v191, v40, v41
	v_cvt_pk_bf16_f32 v192, v34, v35
	v_cvt_pk_bf16_f32 v193, v36, v37
	v_add_u32_e32 v255, 0x129000, v245
	global_store_dwordx4 v255, v[190:193], s[98:99] offset:256
	v_fmac_f32_e32 v247, v38, v38
	v_fmac_f32_e32 v247, v39, v39
	v_fmac_f32_e32 v247, v40, v40
	v_fmac_f32_e32 v247, v41, v41
	v_fmac_f32_e32 v254, v34, v34
	v_fmac_f32_e32 v254, v35, v35
	v_fmac_f32_e32 v254, v36, v36
	v_fmac_f32_e32 v254, v37, v37
	v_add_f32_e32 v46, v247, v254
	s_waitcnt vmcnt(15)
	v_lshlrev_b32_e32 v248, 16, v194
	v_and_b32_e32 v249, 0xffff0000, v194
	v_lshlrev_b32_e32 v250, 16, v195
	v_and_b32_e32 v251, 0xffff0000, v195
	v_pk_add_f32 v[30:31], v[30:31], v[248:249]
	v_pk_add_f32 v[32:33], v[32:33], v[250:251]
	v_lshlrev_b32_e32 v248, 16, v196
	v_and_b32_e32 v249, 0xffff0000, v196
	v_lshlrev_b32_e32 v250, 16, v197
	v_and_b32_e32 v251, 0xffff0000, v197
	v_pk_add_f32 v[26:27], v[26:27], v[248:249]
	v_pk_add_f32 v[28:29], v[28:29], v[250:251]
	v_cvt_pk_bf16_f32 v194, v30, v31
	v_cvt_pk_bf16_f32 v195, v32, v33
	v_cvt_pk_bf16_f32 v196, v26, v27
	v_cvt_pk_bf16_f32 v197, v28, v29
	v_add_u32_e32 v246, 0x14a000, v245
	global_store_dwordx4 v246, v[194:197], s[98:99]
	v_mul_f32_e32 v247, v30, v30
	v_fmac_f32_e32 v247, v31, v31
	v_fmac_f32_e32 v247, v32, v32
	v_fmac_f32_e32 v247, v33, v33
	v_mul_f32_e32 v254, v26, v26
	v_fmac_f32_e32 v254, v27, v27
	v_fmac_f32_e32 v254, v28, v28
	v_fmac_f32_e32 v254, v29, v29
	s_waitcnt vmcnt(15)
	v_lshlrev_b32_e32 v248, 16, v198
	v_and_b32_e32 v249, 0xffff0000, v198
	v_lshlrev_b32_e32 v250, 16, v199
	v_and_b32_e32 v251, 0xffff0000, v199
	v_pk_add_f32 v[22:23], v[22:23], v[248:249]
	v_pk_add_f32 v[24:25], v[24:25], v[250:251]
	v_lshlrev_b32_e32 v248, 16, v200
	v_and_b32_e32 v249, 0xffff0000, v200
	v_lshlrev_b32_e32 v250, 16, v201
	v_and_b32_e32 v251, 0xffff0000, v201
	v_pk_add_f32 v[18:19], v[18:19], v[248:249]
	v_pk_add_f32 v[20:21], v[20:21], v[250:251]
	v_cvt_pk_bf16_f32 v198, v22, v23
	v_cvt_pk_bf16_f32 v199, v24, v25
	v_cvt_pk_bf16_f32 v200, v18, v19
	v_cvt_pk_bf16_f32 v201, v20, v21
	v_add_u32_e32 v255, 0x14a000, v245
	global_store_dwordx4 v255, v[198:201], s[98:99] offset:256
	v_fmac_f32_e32 v247, v22, v22
	v_fmac_f32_e32 v247, v23, v23
	v_fmac_f32_e32 v247, v24, v24
	v_fmac_f32_e32 v247, v25, v25
	v_fmac_f32_e32 v254, v18, v18
	v_fmac_f32_e32 v254, v19, v19
	v_fmac_f32_e32 v254, v20, v20
	v_fmac_f32_e32 v254, v21, v21
	v_add_f32_e32 v30, v247, v254
	s_waitcnt vmcnt(15)
; __device__ __forceinline__ unsigned cvt_pk_bf16(float lo, float hi) { unsigned r; asm volatile("v_cvt_pk_bf16_f32 %0, %1, %2" : "=v"(r) : "v"(lo), "v"(hi)); return r; }
; __device__ __forceinline__ float bf_lo(unsigned w) { return __uint_as_float(w << 16); }
;     __device__ __forceinline__ void operator()(EPI_ARGS) const {
;     ...
;             for (int m = 0; m < 4; ++m) { const int row = row0 + ai * HALF + m * 16; const size_t off = (size_t)row * ldc + col0; float ss = 0.f, mx = 0.f;
; #pragma unroll
;                 for (int bj = 0; bj < 2; ++bj) {
;                     f32x4 a0, a1;
;                     if (RES_BF16) { const u32x4 rw = __builtin_bit_cast(u32x4, r0[m][bj]); a0 = (f32x4){bf_lo(rw.x), bf_hi(rw.x), bf_lo(rw.y), bf_hi(rw.y)}; a1 = (f32x4){bf_lo(rw.z), bf_hi(rw.z), bf_lo(rw.w), bf_hi(rw.w)};
;                         if (RES_SCALE) { const float rf = rfac[row]; a0 = a0 * rf; a1 = a1 * rf; } }
;                     else { a0 = r0[m][bj]; a1 = r1[m][bj]; }
;                     const f32x4 v0 = acc[ai][bj][m][0] + a0, v1 = acc[ai][bj][m][1] + a1;
;                     u32x4 w; w.x = cvt_pk_bf16(v0[0], v0[1]); w.y = cvt_pk_bf16(v0[2], v0[3]); w.z = cvt_pk_bf16(v1[0], v1[1]); w.w = cvt_pk_bf16(v1[2], v1[3]); *(u32x4*)(ob + off + bj * HALF) = w;
;                     ss += (v0[0] * v0[0] + v0[1] * v0[1]) + (v0[2] * v0[2] + v0[3] * v0[3]) + (v1[0] * v1[0] + v1[1] * v1[1]) + (v1[2] * v1[2] + v1[3] * v1[3]);
;                     if (rowmax) mx = fmaxf(mx, fmaxf(fmaxf(fmaxf(fabsf(v0[0]), fabsf(v0[1])), fmaxf(fabsf(v0[2]), fabsf(v0[3]))), fmaxf(fmaxf(fabsf(v1[0]), fabsf(v1[1])), fmaxf(fabsf(v1[2]), fabsf(v1[3]))))); }
;                 ss += __shfl_xor(ss, 16); ss += __shfl_xor(ss, 32); ssv[ai * 4 + m] = ss;
;                 if (rowmax) { mx = fmaxf(mx, __shfl_xor(mx, 16)); mx = fmaxf(mx, __shfl_xor(mx, 32)); } mxv[ai * 4 + m] = mx; }
;             asm volatile("" ::: "memory"); }
;         float s0 = 0.f, s1 = 0.f, m0 = 0.f, m1 = 0.f;
; #pragma unroll
;         for (int k = 0; k < 8; ++k) if ((k >> 1) == fq) { if (k & 1) { s1 = ssv[k]; m1 = mxv[k]; } else { s0 = ssv[k]; m0 = mxv[k]; } }
;         const int rq = row0 + (fq >> 1) * HALF + (fq & 1) * 32;
;         __hip_atomic_fetch_add(rowsq + rq, s0, __ATOMIC_RELAXED, __HIP_MEMORY_SCOPE_AGENT); __hip_atomic_fetch_add(rowsq + rq + 16, s1, __ATOMIC_RELAXED, __HIP_MEMORY_SCOPE_AGENT);
	v_lshlrev_b32_e32 v248, 16, v202
	v_and_b32_e32 v249, 0xffff0000, v202
	v_lshlrev_b32_e32 v250, 16, v203
	v_and_b32_e32 v251, 0xffff0000, v203
	v_pk_add_f32 v[14:15], v[14:15], v[248:249]
	v_pk_add_f32 v[16:17], v[16:17], v[250:251]
	v_lshlrev_b32_e32 v248, 16, v204
	v_and_b32_e32 v249, 0xffff0000, v204
	v_lshlrev_b32_e32 v250, 16, v205
	v_and_b32_e32 v251, 0xffff0000, v205
	v_pk_add_f32 v[10:11], v[10:11], v[248:249]
	v_pk_add_f32 v[12:13], v[12:13], v[250:251]
	v_cvt_pk_bf16_f32 v202, v14, v15
	v_cvt_pk_bf16_f32 v203, v16, v17
	v_cvt_pk_bf16_f32 v204, v10, v11
	v_cvt_pk_bf16_f32 v205, v12, v13
	v_add_u32_e32 v246, 0x16b000, v245
	global_store_dwordx4 v246, v[202:205], s[98:99]
	v_mul_f32_e32 v247, v14, v14
	v_fmac_f32_e32 v247, v15, v15
	v_fmac_f32_e32 v247, v16, v16
	v_fmac_f32_e32 v247, v17, v17
	v_mul_f32_e32 v254, v10, v10
	v_fmac_f32_e32 v254, v11, v11
	v_fmac_f32_e32 v254, v12, v12
	v_fmac_f32_e32 v254, v13, v13
	s_waitcnt vmcnt(15)
	v_lshlrev_b32_e32 v248, 16, v206
	v_and_b32_e32 v249, 0xffff0000, v206
	v_lshlrev_b32_e32 v250, 16, v207
	v_and_b32_e32 v251, 0xffff0000, v207
	v_pk_add_f32 v[6:7], v[6:7], v[248:249]
	v_pk_add_f32 v[8:9], v[8:9], v[250:251]
	v_lshlrev_b32_e32 v248, 16, v208
	v_and_b32_e32 v249, 0xffff0000, v208
	v_lshlrev_b32_e32 v250, 16, v209
	v_and_b32_e32 v251, 0xffff0000, v209
	v_pk_add_f32 v[2:3], v[2:3], v[248:249]
	v_pk_add_f32 v[4:5], v[4:5], v[250:251]
	v_cvt_pk_bf16_f32 v206, v6, v7
	v_cvt_pk_bf16_f32 v207, v8, v9
	v_cvt_pk_bf16_f32 v208, v2, v3
	v_cvt_pk_bf16_f32 v209, v4, v5
	v_add_u32_e32 v255, 0x16b000, v245
	global_store_dwordx4 v255, v[206:209], s[98:99] offset:256
	v_fmac_f32_e32 v247, v6, v6
	v_fmac_f32_e32 v247, v7, v7
	v_fmac_f32_e32 v247, v8, v8
	v_fmac_f32_e32 v247, v9, v9
	v_fmac_f32_e32 v254, v2, v2
	v_fmac_f32_e32 v254, v3, v3
	v_fmac_f32_e32 v254, v4, v4
	v_fmac_f32_e32 v254, v5, v5
	v_add_f32_e32 v14, v247, v254
	v_and_b32_e32 v255, 63, v0
	v_xor_b32_e32 v252, 16, v255
	v_xor_b32_e32 v253, 32, v255
	v_lshlrev_b32_e32 v252, 2, v252
	v_lshlrev_b32_e32 v253, 2, v253
	ds_bpermute_b32 v127, v252, v126
	ds_bpermute_b32 v111, v252, v110
	ds_bpermute_b32 v95, v252, v94
	ds_bpermute_b32 v79, v252, v78
	ds_bpermute_b32 v63, v252, v62
	ds_bpermute_b32 v47, v252, v46
	ds_bpermute_b32 v31, v252, v30
	ds_bpermute_b32 v15, v252, v14
	s_waitcnt lgkmcnt(0)
	v_add_f32_e32 v126, v126, v127
	v_add_f32_e32 v110, v110, v111
	v_add_f32_e32 v94, v94, v95
	v_add_f32_e32 v78, v78, v79
	v_add_f32_e32 v62, v62, v63
	v_add_f32_e32 v46, v46, v47
	v_add_f32_e32 v30, v30, v31
	v_add_f32_e32 v14, v14, v15
	ds_bpermute_b32 v127, v253, v126
	ds_bpermute_b32 v111, v253, v110
	ds_bpermute_b32 v95, v253, v94
	ds_bpermute_b32 v79, v253, v78
	ds_bpermute_b32 v63, v253, v62
	ds_bpermute_b32 v47, v253, v46
	ds_bpermute_b32 v31, v253, v30
	ds_bpermute_b32 v15, v253, v14
	s_waitcnt lgkmcnt(0)
	v_add_f32_e32 v126, v126, v127
	v_add_f32_e32 v110, v110, v111
	v_add_f32_e32 v94, v94, v95
	v_add_f32_e32 v78, v78, v79
	v_add_f32_e32 v62, v62, v63
	v_add_f32_e32 v46, v46, v47
	v_add_f32_e32 v30, v30, v31
	v_add_f32_e32 v14, v14, v15
	v_cndmask_b32_e64 v248, 0, v126, s[2:3]
	v_cndmask_b32_e64 v249, 0, v110, s[2:3]
	v_cndmask_b32_e64 v248, v248, v94, s[4:5]
	v_cndmask_b32_e64 v249, v249, v78, s[4:5]
	v_cndmask_b32_e64 v248, v248, v62, s[6:7]
	v_cndmask_b32_e64 v249, v249, v46, s[6:7]
	v_cndmask_b32_e64 v248, v248, v30, s[8:9]
	v_cndmask_b32_e64 v249, v249, v14, s[8:9]
	v_lshl_add_u32 v250, s72, 8, v157
	v_add_u32_e32 v250, v158, v250
	v_lshlrev_b32_e32 v250, 2, v250
	global_atomic_add_f32 v250, v248, s[34:35]
	global_atomic_add_f32 v250, v249, s[34:35] offset:64
	s_and_b64 vcc, exec, s[10:11]
	s_mov_b64 s[10:11], -1
	s_cbranch_vccnz .LBB0_1349
	s_andn2_b64 vcc, exec, s[0:1]
	s_cbranch_vccnz .LBB0_1348
	s_barrier
	s_branch .LBB0_1348

; #define GAS __attribute__((address_space(1)))
; __device__ __forceinline__ float row_rstd(const float* rowsq, int row) { return 1.0f / sqrtf(__hip_atomic_load(rowsq + row, __ATOMIC_RELAXED, __HIP_MEMORY_SCOPE_AGENT) * (1.0f / DM) + EPS); }
; #define REPS(k) _Pragma("unroll") for (int rep_ = 0; rep_ <= ((DUP_MASK >> (k)) & 1); ++rep_)
; __global__ void __launch_bounds__(NWAVES * 64, 2) fwd_kernel(Args args) {
;     ...
;         REPS(9) { const bool dup_ = rep_ < ((DUP_MASK >> 9) & 1);
;         f32x4 gv[16];
; #pragma unroll
;         for (int j = 0; j < 16; ++j) gv[j] = *((const GAS f32x4*)g_final + lane + 64 * j);
;         for (int m = gw; m < MTOK; m += 2 * NGW) {
;             const int mb = (m + NGW < MTOK) ? m + NGW : m;
;             const float ra = bad ? __builtin_nanf("") : pg8::row_rstd(rsq3, m), rb = bad ? __builtin_nanf("") : pg8::row_rstd(rsq3, mb);
;             u32x2 ha[16], hb[16];
; #pragma unroll
;             for (int j = 0; j < 16; ++j) { ha[j] = *((const GAS u32x2*)(HB + (size_t)m * DM) + lane + 64 * j); hb[j] = *((const GAS u32x2*)(HB + (size_t)mb * DM) + lane + 64 * j); }
;             GAS f32x4* wa = (GAS f32x4*)((dup_ ? dummy_out : out) + (size_t)m * DM) + lane; GAS f32x4* wb = (GAS f32x4*)((dup_ ? dummy_out : out) + (size_t)mb * DM) + lane;
.LBB0_1422:
	s_cmp_lt_i32 s96, 10
	s_cselect_b64 s[0:1], -1, 0
	s_cmp_gt_i32 s97, 9
	s_cselect_b64 s[2:3], -1, 0
	s_and_b64 s[0:1], s[0:1], s[2:3]
	s_andn2_b64 vcc, exec, s[0:1]
	v_readlane_b32 s0, v244, 2
	v_readlane_b32 s10, v244, 12
	v_readlane_b32 s11, v244, 13
	v_readlane_b32 s12, v244, 14
	v_readlane_b32 s13, v244, 15
	v_readlane_b32 s14, v244, 16
	v_readlane_b32 s15, v244, 17
	v_readlane_b32 s1, v244, 3
	v_readlane_b32 s2, v244, 4
	v_readlane_b32 s3, v244, 5
	v_readlane_b32 s4, v244, 6
	v_readlane_b32 s5, v244, 7
	v_readlane_b32 s6, v244, 8
	v_readlane_b32 s7, v244, 9
	v_readlane_b32 s8, v244, 10
	v_readlane_b32 s9, v244, 11
	s_cbranch_vccnz .LBB0_1432
	s_mov_b64 s[30:31], s[14:15]
	v_mov_b32_e32 v1, 0x4000
	global_load_dword v70, v1, s[30:31] offset:512 sc1
	s_mov_b64 s[28:29], s[12:13]
	s_cmpk_gt_i32 s18, 0x3fff
	s_cbranch_scc1 .LBB0_1432
	v_and_b32_e32 v68, 63, v0
	s_mov_b64 s[26:27], s[10:11]
	s_waitcnt vmcnt(34)
	v_lshlrev_b32_e32 v64, 4, v68
	v_mov_b32_e32 v65, 0
	v_lshl_add_u64 v[48:49], s[26:27], 0, v[64:65]
	v_add_co_u32_e32 v32, vcc, 0x1000, v48
	global_load_dwordx4 v[0:3], v64, s[10:11]
	global_load_dwordx4 v[4:7], v64, s[10:11] offset:1024
	global_load_dwordx4 v[8:11], v64, s[10:11] offset:2048
	global_load_dwordx4 v[12:15], v64, s[10:11] offset:3072
	v_addc_co_u32_e32 v33, vcc, 0, v49, vcc
	v_add_co_u32_e32 v50, vcc, 0x2000, v48
	global_load_dwordx4 v[16:19], v[32:33], off
	global_load_dwordx4 v[20:23], v[32:33], off offset:1024
	global_load_dwordx4 v[24:27], v[32:33], off offset:2048
	global_load_dwordx4 v[28:31], v[32:33], off offset:3072
	v_addc_co_u32_e32 v51, vcc, 0, v49, vcc
	v_add_co_u32_e32 v66, vcc, 0x3000, v48
	global_load_dwordx4 v[32:35], v[50:51], off
	global_load_dwordx4 v[36:39], v[50:51], off offset:1024
	global_load_dwordx4 v[40:43], v[50:51], off offset:2048
	global_load_dwordx4 v[44:47], v[50:51], off offset:3072
	v_addc_co_u32_e32 v67, vcc, 0, v49, vcc
	global_load_dwordx4 v[48:51], v[66:67], off
	global_load_dwordx4 v[52:55], v[66:67], off offset:1024
	global_load_dwordx4 v[56:59], v[66:67], off offset:2048
	global_load_dwordx4 v[60:63], v[66:67], off offset:3072
	s_ashr_i32 s19, s18, 31
	s_lshl_b32 s6, s22, 4
	s_lshl_b64 s[2:3], s[18:19], 14
	s_add_u32 s2, s28, s2
	s_addc_u32 s3, s29, s3
	s_waitcnt vmcnt(16)
	v_cmp_eq_u32_e64 s[0:1], 0, v70
	v_lshl_add_u64 v[70:71], s[2:3], 0, v[64:65]
	s_mov_b64 s[2:3], 0x3c00
	s_ashr_i32 s7, s6, 31
	v_lshl_add_u64 v[70:71], v[70:71], 0, s[2:3]
	s_lshl_b64 s[8:9], s[6:7], 14
	s_lshl_b64 s[2:3], s[18:19], 2
	s_add_u32 s17, s2, 0x60000
	v_lshlrev_b32_e32 v72, 3, v68
	v_mov_b32_e32 v73, v65
	s_addc_u32 s21, s3, 0
	s_mul_i32 s2, s18, 0x2100
	s_mov_b32 s3, 0
	v_lshl_add_u64 v[66:67], s[98:99], 0, v[72:73]
	v_lshl_add_u64 v[68:69], s[28:29], 0, v[64:65]
	s_movk_i32 s14, 0x1000
	s_movk_i32 s15, 0x2000
	s_movk_i32 s16, 0x3000
	s_lshl_b64 s[10:11], s[6:7], 2
	v_add_u32_e32 v72, s2, v72
	v_mov_b32_e32 v73, s3
	s_mul_i32 s12, s6, 0x2100
	s_mov_b32 s13, 0
	v_mov_b32_e32 v93, 0x358637bd
	s_mov_b32 s7, 0xf800000
	v_mov_b32_e32 v116, 0x260
	s_mov_b32 s19, 0x3a601000
	s_movk_i32 s22, 0xd000
	s_movk_i32 s23, 0xe000
	s_movk_i32 s24, 0xf000
	s_branch .LBB0_1426

; #define GAS __attribute__((address_space(1)))
; __device__ __forceinline__ float bf_lo(unsigned w) { return __uint_as_float(w << 16); }
; __device__ __forceinline__ float bf_hi(unsigned w) { return __uint_as_float(w & 0xffff0000u); }
; __device__ __forceinline__ float row_rstd(const float* rowsq, int row) { return 1.0f / sqrtf(__hip_atomic_load(rowsq + row, __ATOMIC_RELAXED, __HIP_MEMORY_SCOPE_AGENT) * (1.0f / DM) + EPS); }
; __global__ void __launch_bounds__(NWAVES * 64, 2) fwd_kernel(Args args) {
;     ...
;         for (int m = gw; m < MTOK; m += 2 * NGW) {
;             const int mb = (m + NGW < MTOK) ? m + NGW : m;
;             const float ra = bad ? __builtin_nanf("") : pg8::row_rstd(rsq3, m), rb = bad ? __builtin_nanf("") : pg8::row_rstd(rsq3, mb);
;             u32x2 ha[16], hb[16];
; #pragma unroll
;             for (int j = 0; j < 16; ++j) { ha[j] = *((const GAS u32x2*)(HB + (size_t)m * DM) + lane + 64 * j); hb[j] = *((const GAS u32x2*)(HB + (size_t)mb * DM) + lane + 64 * j); }
;             GAS f32x4* wa = (GAS f32x4*)((dup_ ? dummy_out : out) + (size_t)m * DM) + lane; GAS f32x4* wb = (GAS f32x4*)((dup_ ? dummy_out : out) + (size_t)mb * DM) + lane;
; #pragma unroll
;             for (int j = 0; j < 16; ++j) wa[64 * j] = (f32x4){bf_lo(ha[j].x), bf_hi(ha[j].x), bf_lo(ha[j].y), bf_hi(ha[j].y)} * ra * gv[j];
;             if (mb != m) {
; #pragma unroll
;                 for (int j = 0; j < 16; ++j) wb[64 * j] = (f32x4){bf_lo(hb[j].x), bf_hi(hb[j].x), bf_lo(hb[j].y), bf_hi(hb[j].y)} * rb * gv[j]; }
.LBB0_1430:
	s_waitcnt vmcnt(16)
	v_lshl_add_u64 v[74:75], s[30:31], 0, v[72:73]
	v_add_co_u32_e32 v76, vcc, 0x3a600000, v74
	s_mul_i32 s2, s4, 0x2100
	s_mov_b32 s3, 0
	s_nop 0
	v_addc_co_u32_e32 v77, vcc, 0, v75, vcc
	global_load_dwordx2 v[118:119], v[76:77], off
	global_load_dwordx2 v[120:121], v[76:77], off offset:512
	global_load_dwordx2 v[122:123], v[76:77], off offset:1024
	global_load_dwordx2 v[124:125], v[76:77], off offset:1536
	global_load_dwordx2 v[134:135], v[76:77], off offset:2048
	v_lshl_add_u64 v[78:79], v[66:67], 0, s[2:3]
	global_load_dwordx2 v[138:139], v[76:77], off offset:2560
	global_load_dwordx2 v[106:107], v[78:79], off
	global_load_dwordx2 v[104:105], v[78:79], off offset:512
	global_load_dwordx2 v[102:103], v[78:79], off offset:1024
	global_load_dwordx2 v[100:101], v[78:79], off offset:1536
	global_load_dwordx2 v[98:99], v[78:79], off offset:2048
	global_load_dwordx2 v[96:97], v[78:79], off offset:2560
	global_load_dwordx2 v[94:95], v[78:79], off offset:3072
	global_load_dwordx2 v[90:91], v[78:79], off offset:3584
	global_load_dwordx2 v[140:141], v[76:77], off offset:3072
	v_add_co_u32_e32 v136, vcc, s22, v70
	s_cmp_eq_u32 s18, s4
	s_nop 0
	v_addc_co_u32_e32 v137, vcc, -1, v71, vcc
	v_add_co_u32_e32 v74, vcc, s19, v74
	s_waitcnt vmcnt(13)
	v_lshlrev_b32_e32 v128, 16, v120
	v_addc_co_u32_e32 v75, vcc, 0, v75, vcc
	v_add_co_u32_e32 v126, vcc, s14, v78
	v_and_b32_e32 v129, 0xffff0000, v120
	s_nop 0
	v_addc_co_u32_e32 v127, vcc, 0, v79, vcc
	global_load_dwordx2 v[142:143], v[74:75], off
	global_load_dwordx2 v[144:145], v[74:75], off offset:512
	global_load_dwordx2 v[146:147], v[74:75], off offset:1024
	global_load_dwordx2 v[148:149], v[74:75], off offset:1536
	global_load_dwordx2 v[150:151], v[76:77], off offset:3584
	global_load_dwordx2 v[114:115], v[74:75], off offset:2048
	global_load_dwordx2 v[112:113], v[74:75], off offset:2560
	global_load_dwordx2 v[110:111], v[74:75], off offset:3072
	global_load_dwordx2 v[108:109], v[74:75], off offset:3584
	global_load_dwordx2 v[88:89], v[126:127], off
	global_load_dwordx2 v[86:87], v[126:127], off offset:512
	global_load_dwordx2 v[84:85], v[126:127], off offset:1024
	global_load_dwordx2 v[82:83], v[126:127], off offset:1536
	global_load_dwordx2 v[80:81], v[126:127], off offset:2048
	global_load_dwordx2 v[78:79], v[126:127], off offset:2560
	global_load_dwordx2 v[76:77], v[126:127], off offset:3072
	global_load_dwordx2 v[74:75], v[126:127], off offset:3584
	v_lshlrev_b32_e32 v126, 16, v118
	v_and_b32_e32 v127, 0xffff0000, v118
	v_lshlrev_b32_e32 v118, 16, v119
	v_and_b32_e32 v119, 0xffff0000, v119
	v_lshlrev_b32_e32 v120, 16, v121
	v_and_b32_e32 v121, 0xffff0000, v121
	s_waitcnt vmcnt(29)
	v_lshlrev_b32_e32 v130, 16, v122
	v_and_b32_e32 v131, 0xffff0000, v122
	v_lshlrev_b32_e32 v122, 16, v123
	v_and_b32_e32 v123, 0xffff0000, v123
	v_pk_mul_f32 v[126:127], v[92:93], v[126:127] op_sel_hi:[0,1]
	v_pk_mul_f32 v[118:119], v[92:93], v[118:119] op_sel_hi:[0,1]
	s_waitcnt vmcnt(28)
	v_lshlrev_b32_e32 v132, 16, v124
	v_and_b32_e32 v133, 0xffff0000, v124
	v_lshlrev_b32_e32 v124, 16, v125
	v_and_b32_e32 v125, 0xffff0000, v125
	v_pk_mul_f32 v[128:129], v[92:93], v[128:129] op_sel_hi:[0,1]
	v_pk_mul_f32 v[152:153], v[92:93], v[120:121] op_sel_hi:[0,1]
	v_pk_mul_f32 v[130:131], v[92:93], v[130:131] op_sel_hi:[0,1]
	v_pk_mul_f32 v[154:155], v[92:93], v[122:123] op_sel_hi:[0,1]
	v_pk_mul_f32 v[120:121], v[2:3], v[118:119]
	v_pk_mul_f32 v[118:119], v[0:1], v[126:127]
	v_pk_mul_f32 v[156:157], v[92:93], v[132:133] op_sel_hi:[0,1]
	v_pk_mul_f32 v[132:133], v[92:93], v[124:125] op_sel_hi:[0,1]
	v_pk_mul_f32 v[124:125], v[6:7], v[152:153]
	v_pk_mul_f32 v[122:123], v[4:5], v[128:129]
	v_pk_mul_f32 v[128:129], v[10:11], v[154:155]
	v_pk_mul_f32 v[126:127], v[8:9], v[130:131]
	global_store_dwordx4 v[136:137], v[118:121], off offset:-3072
	global_store_dwordx4 v[136:137], v[122:125], off offset:-2048
	global_store_dwordx4 v[136:137], v[126:129], off offset:-1024
	s_waitcnt vmcnt(30)
	v_lshlrev_b32_e32 v118, 16, v134
	v_and_b32_e32 v119, 0xffff0000, v134
	v_lshlrev_b32_e32 v120, 16, v135
	v_and_b32_e32 v121, 0xffff0000, v135
	v_add_co_u32_e32 v122, vcc, s23, v70
	v_pk_mul_f32 v[118:119], v[92:93], v[118:119] op_sel_hi:[0,1]
	v_pk_mul_f32 v[120:121], v[92:93], v[120:121] op_sel_hi:[0,1]
	v_addc_co_u32_e32 v123, vcc, -1, v71, vcc
	v_pk_mul_f32 v[120:121], v[18:19], v[120:121]
	v_pk_mul_f32 v[118:119], v[16:17], v[118:119]
	global_store_dwordx4 v[122:123], v[118:121], off offset:-3072
	v_pk_mul_f32 v[132:133], v[14:15], v[132:133]
	v_pk_mul_f32 v[130:131], v[12:13], v[156:157]
	s_waitcnt vmcnt(30)
	v_lshlrev_b32_e32 v118, 16, v138
	v_and_b32_e32 v119, 0xffff0000, v138
	v_lshlrev_b32_e32 v120, 16, v139
	v_and_b32_e32 v121, 0xffff0000, v139
	v_pk_mul_f32 v[118:119], v[92:93], v[118:119] op_sel_hi:[0,1]
	v_pk_mul_f32 v[120:121], v[92:93], v[120:121] op_sel_hi:[0,1]
	v_pk_mul_f32 v[120:121], v[22:23], v[120:121]
	v_pk_mul_f32 v[118:119], v[20:21], v[118:119]
	global_store_dwordx4 v[122:123], v[118:121], off offset:-2048
	global_store_dwordx4 v[122:123], v[130:133], off offset:-4096
	s_waitcnt vmcnt(23)
	v_lshlrev_b32_e32 v118, 16, v140
	v_and_b32_e32 v119, 0xffff0000, v140
	v_lshlrev_b32_e32 v120, 16, v141
	v_and_b32_e32 v121, 0xffff0000, v141
	v_pk_mul_f32 v[118:119], v[92:93], v[118:119] op_sel_hi:[0,1]
	v_pk_mul_f32 v[120:121], v[92:93], v[120:121] op_sel_hi:[0,1]
	v_pk_mul_f32 v[120:121], v[26:27], v[120:121]
	v_pk_mul_f32 v[118:119], v[24:25], v[118:119]
	global_store_dwordx4 v[122:123], v[118:121], off offset:-1024
	s_waitcnt vmcnt(19)
; #define GAS __attribute__((address_space(1)))
; __device__ __forceinline__ float bf_lo(unsigned w) { return __uint_as_float(w << 16); }
; __device__ __forceinline__ float bf_hi(unsigned w) { return __uint_as_float(w & 0xffff0000u); }
; __device__ __forceinline__ float row_rstd(const float* rowsq, int row) { return 1.0f / sqrtf(__hip_atomic_load(rowsq + row, __ATOMIC_RELAXED, __HIP_MEMORY_SCOPE_AGENT) * (1.0f / DM) + EPS); }
; __global__ void __launch_bounds__(NWAVES * 64, 2) fwd_kernel(Args args) {
;     ...
;         for (int m = gw; m < MTOK; m += 2 * NGW) {
;             const int mb = (m + NGW < MTOK) ? m + NGW : m;
;             const float ra = bad ? __builtin_nanf("") : pg8::row_rstd(rsq3, m), rb = bad ? __builtin_nanf("") : pg8::row_rstd(rsq3, mb);
;             u32x2 ha[16], hb[16];
; #pragma unroll
;             for (int j = 0; j < 16; ++j) { ha[j] = *((const GAS u32x2*)(HB + (size_t)m * DM) + lane + 64 * j); hb[j] = *((const GAS u32x2*)(HB + (size_t)mb * DM) + lane + 64 * j); }
;             GAS f32x4* wa = (GAS f32x4*)((dup_ ? dummy_out : out) + (size_t)m * DM) + lane; GAS f32x4* wb = (GAS f32x4*)((dup_ ? dummy_out : out) + (size_t)mb * DM) + lane;
; #pragma unroll
;             for (int j = 0; j < 16; ++j) wa[64 * j] = (f32x4){bf_lo(ha[j].x), bf_hi(ha[j].x), bf_lo(ha[j].y), bf_hi(ha[j].y)} * ra * gv[j];
;             if (mb != m) {
; #pragma unroll
;                 for (int j = 0; j < 16; ++j) wb[64 * j] = (f32x4){bf_lo(hb[j].x), bf_hi(hb[j].x), bf_lo(hb[j].y), bf_hi(hb[j].y)} * rb * gv[j]; }
	s_nop 0
	v_lshlrev_b32_e32 v118, 16, v150
	v_and_b32_e32 v119, 0xffff0000, v150
	v_lshlrev_b32_e32 v120, 16, v151
	v_and_b32_e32 v121, 0xffff0000, v151
	v_pk_mul_f32 v[118:119], v[92:93], v[118:119] op_sel_hi:[0,1]
	v_pk_mul_f32 v[120:121], v[92:93], v[120:121] op_sel_hi:[0,1]
	v_pk_mul_f32 v[120:121], v[30:31], v[120:121]
	v_pk_mul_f32 v[118:119], v[28:29], v[118:119]
	global_store_dwordx4 v[122:123], v[118:121], off
	v_add_co_u32_e32 v122, vcc, s24, v70
	s_nop 0
	v_lshlrev_b32_e32 v118, 16, v142
	v_and_b32_e32 v119, 0xffff0000, v142
	v_lshlrev_b32_e32 v120, 16, v143
	v_and_b32_e32 v121, 0xffff0000, v143
	v_pk_mul_f32 v[118:119], v[92:93], v[118:119] op_sel_hi:[0,1]
	v_pk_mul_f32 v[120:121], v[92:93], v[120:121] op_sel_hi:[0,1]
	v_pk_mul_f32 v[120:121], v[34:35], v[120:121]
	v_pk_mul_f32 v[118:119], v[32:33], v[118:119]
	v_addc_co_u32_e32 v123, vcc, -1, v71, vcc
	global_store_dwordx4 v[122:123], v[118:121], off offset:-3072
	s_nop 1
	v_lshlrev_b32_e32 v118, 16, v144
	v_and_b32_e32 v119, 0xffff0000, v144
	v_lshlrev_b32_e32 v120, 16, v145
	v_and_b32_e32 v121, 0xffff0000, v145
	v_pk_mul_f32 v[118:119], v[92:93], v[118:119] op_sel_hi:[0,1]
	v_pk_mul_f32 v[120:121], v[92:93], v[120:121] op_sel_hi:[0,1]
	v_pk_mul_f32 v[120:121], v[38:39], v[120:121]
	v_pk_mul_f32 v[118:119], v[36:37], v[118:119]
	global_store_dwordx4 v[122:123], v[118:121], off offset:-2048
	s_nop 1
	v_lshlrev_b32_e32 v118, 16, v146
	v_and_b32_e32 v119, 0xffff0000, v146
	v_lshlrev_b32_e32 v120, 16, v147
	v_and_b32_e32 v121, 0xffff0000, v147
	v_pk_mul_f32 v[118:119], v[92:93], v[118:119] op_sel_hi:[0,1]
	v_pk_mul_f32 v[120:121], v[92:93], v[120:121] op_sel_hi:[0,1]
	v_pk_mul_f32 v[120:121], v[42:43], v[120:121]
	v_pk_mul_f32 v[118:119], v[40:41], v[118:119]
	global_store_dwordx4 v[122:123], v[118:121], off offset:-1024
	s_nop 1
	v_lshlrev_b32_e32 v118, 16, v148
	v_and_b32_e32 v119, 0xffff0000, v148
	v_lshlrev_b32_e32 v120, 16, v149
	v_and_b32_e32 v121, 0xffff0000, v149
	v_pk_mul_f32 v[118:119], v[92:93], v[118:119] op_sel_hi:[0,1]
	v_pk_mul_f32 v[120:121], v[92:93], v[120:121] op_sel_hi:[0,1]
	v_pk_mul_f32 v[120:121], v[46:47], v[120:121]
	v_pk_mul_f32 v[118:119], v[44:45], v[118:119]
	global_store_dwordx4 v[70:71], v[118:121], off offset:-4096
	s_waitcnt vmcnt(23)
	s_nop 0
	v_lshlrev_b32_e32 v118, 16, v114
	v_and_b32_e32 v119, 0xffff0000, v114
	v_lshlrev_b32_e32 v114, 16, v115
	v_and_b32_e32 v115, 0xffff0000, v115
	v_pk_mul_f32 v[118:119], v[92:93], v[118:119] op_sel_hi:[0,1]
	v_pk_mul_f32 v[114:115], v[92:93], v[114:115] op_sel_hi:[0,1]
	v_pk_mul_f32 v[120:121], v[50:51], v[114:115]
	v_pk_mul_f32 v[118:119], v[48:49], v[118:119]
	s_waitcnt vmcnt(22)
	v_lshlrev_b32_e32 v114, 16, v112
	v_and_b32_e32 v115, 0xffff0000, v112
	v_lshlrev_b32_e32 v112, 16, v113
	v_and_b32_e32 v113, 0xffff0000, v113
	global_store_dwordx4 v[70:71], v[118:121], off offset:-3072
	v_pk_mul_f32 v[112:113], v[92:93], v[112:113] op_sel_hi:[0,1]
	s_nop 0
	v_pk_mul_f32 v[118:119], v[92:93], v[114:115] op_sel_hi:[0,1]
	v_pk_mul_f32 v[114:115], v[54:55], v[112:113]
	v_pk_mul_f32 v[112:113], v[52:53], v[118:119]
	global_store_dwordx4 v[70:71], v[112:115], off offset:-2048
	s_waitcnt vmcnt(23)
	s_nop 0
	v_lshlrev_b32_e32 v112, 16, v110
	v_and_b32_e32 v113, 0xffff0000, v110
	v_lshlrev_b32_e32 v110, 16, v111
	v_and_b32_e32 v111, 0xffff0000, v111
	v_pk_mul_f32 v[114:115], v[92:93], v[112:113] op_sel_hi:[0,1]
	v_pk_mul_f32 v[110:111], v[92:93], v[110:111] op_sel_hi:[0,1]
	v_pk_mul_f32 v[112:113], v[58:59], v[110:111]
	v_pk_mul_f32 v[110:111], v[56:57], v[114:115]
	global_store_dwordx4 v[70:71], v[110:113], off offset:-1024
	s_waitcnt vmcnt(23)
	s_nop 0
	v_lshlrev_b32_e32 v110, 16, v108
	v_and_b32_e32 v111, 0xffff0000, v108
	v_lshlrev_b32_e32 v108, 16, v109
	v_and_b32_e32 v109, 0xffff0000, v109
	v_pk_mul_f32 v[112:113], v[92:93], v[110:111] op_sel_hi:[0,1]
	v_pk_mul_f32 v[108:109], v[92:93], v[108:109] op_sel_hi:[0,1]
	v_pk_mul_f32 v[110:111], v[62:63], v[108:109]
	v_pk_mul_f32 v[108:109], v[60:61], v[112:113]
	global_store_dwordx4 v[70:71], v[108:111], off
	s_cbranch_scc1 .LBB0_1425
	s_nop 0
	v_lshlrev_b32_e32 v108, 16, v106
	v_and_b32_e32 v109, 0xffff0000, v106
	v_lshlrev_b32_e32 v106, 16, v107
	v_and_b32_e32 v107, 0xffff0000, v107
	s_lshl_b64 s[2:3], s[4:5], 14
	v_pk_mul_f32 v[112:113], v[64:65], v[108:109] op_sel_hi:[0,1]
	v_pk_mul_f32 v[106:107], v[64:65], v[106:107] op_sel_hi:[0,1]
	v_lshl_add_u64 v[110:111], v[68:69], 0, s[2:3]
	v_pk_mul_f32 v[108:109], v[2:3], v[106:107]
	v_pk_mul_f32 v[106:107], v[0:1], v[112:113]
	global_store_dwordx4 v[110:111], v[106:109], off
	s_nop 1
	v_lshlrev_b32_e32 v106, 16, v104
	v_and_b32_e32 v107, 0xffff0000, v104
	v_lshlrev_b32_e32 v104, 16, v105
	v_and_b32_e32 v105, 0xffff0000, v105
	v_pk_mul_f32 v[108:109], v[64:65], v[106:107] op_sel_hi:[0,1]
	v_pk_mul_f32 v[104:105], v[64:65], v[104:105] op_sel_hi:[0,1]
	v_pk_mul_f32 v[106:107], v[6:7], v[104:105]
	v_pk_mul_f32 v[104:105], v[4:5], v[108:109]
	global_store_dwordx4 v[110:111], v[104:107], off offset:1024
	s_nop 1
	v_lshlrev_b32_e32 v104, 16, v102
	v_and_b32_e32 v105, 0xffff0000, v102
	v_lshlrev_b32_e32 v102, 16, v103
	v_and_b32_e32 v103, 0xffff0000, v103
	v_pk_mul_f32 v[106:107], v[64:65], v[104:105] op_sel_hi:[0,1]
	v_pk_mul_f32 v[102:103], v[64:65], v[102:103] op_sel_hi:[0,1]
	v_pk_mul_f32 v[104:105], v[10:11], v[102:103]
	v_pk_mul_f32 v[102:103], v[8:9], v[106:107]
	global_store_dwordx4 v[110:111], v[102:105], off offset:2048
	s_nop 1
	v_lshlrev_b32_e32 v102, 16, v100
	v_and_b32_e32 v103, 0xffff0000, v100
	v_lshlrev_b32_e32 v100, 16, v101
	v_and_b32_e32 v101, 0xffff0000, v101
; #define GAS __attribute__((address_space(1)))
; __device__ __forceinline__ float bf_lo(unsigned w) { return __uint_as_float(w << 16); }
; __device__ __forceinline__ float bf_hi(unsigned w) { return __uint_as_float(w & 0xffff0000u); }
; __device__ __forceinline__ float row_rstd(const float* rowsq, int row) { return 1.0f / sqrtf(__hip_atomic_load(rowsq + row, __ATOMIC_RELAXED, __HIP_MEMORY_SCOPE_AGENT) * (1.0f / DM) + EPS); }
; __global__ void __launch_bounds__(NWAVES * 64, 2) fwd_kernel(Args args) {
;     ...
;         for (int m = gw; m < MTOK; m += 2 * NGW) {
;             const int mb = (m + NGW < MTOK) ? m + NGW : m;
;             const float ra = bad ? __builtin_nanf("") : pg8::row_rstd(rsq3, m), rb = bad ? __builtin_nanf("") : pg8::row_rstd(rsq3, mb);
;             u32x2 ha[16], hb[16];
; #pragma unroll
;             for (int j = 0; j < 16; ++j) { ha[j] = *((const GAS u32x2*)(HB + (size_t)m * DM) + lane + 64 * j); hb[j] = *((const GAS u32x2*)(HB + (size_t)mb * DM) + lane + 64 * j); }
;             GAS f32x4* wa = (GAS f32x4*)((dup_ ? dummy_out : out) + (size_t)m * DM) + lane; GAS f32x4* wb = (GAS f32x4*)((dup_ ? dummy_out : out) + (size_t)mb * DM) + lane;
; #pragma unroll
;             for (int j = 0; j < 16; ++j) wa[64 * j] = (f32x4){bf_lo(ha[j].x), bf_hi(ha[j].x), bf_lo(ha[j].y), bf_hi(ha[j].y)} * ra * gv[j];
;             if (mb != m) {
; #pragma unroll
;                 for (int j = 0; j < 16; ++j) wb[64 * j] = (f32x4){bf_lo(hb[j].x), bf_hi(hb[j].x), bf_lo(hb[j].y), bf_hi(hb[j].y)} * rb * gv[j]; }
	v_pk_mul_f32 v[104:105], v[64:65], v[102:103] op_sel_hi:[0,1]
	v_pk_mul_f32 v[100:101], v[64:65], v[100:101] op_sel_hi:[0,1]
	v_pk_mul_f32 v[102:103], v[14:15], v[100:101]
	v_pk_mul_f32 v[100:101], v[12:13], v[104:105]
	global_store_dwordx4 v[110:111], v[100:103], off offset:3072
	s_nop 1
	v_lshlrev_b32_e32 v100, 16, v98
	v_and_b32_e32 v101, 0xffff0000, v98
	v_lshlrev_b32_e32 v98, 16, v99
	v_and_b32_e32 v99, 0xffff0000, v99
	v_pk_mul_f32 v[102:103], v[64:65], v[100:101] op_sel_hi:[0,1]
	v_pk_mul_f32 v[98:99], v[64:65], v[98:99] op_sel_hi:[0,1]
	v_pk_mul_f32 v[100:101], v[18:19], v[98:99]
	v_pk_mul_f32 v[98:99], v[16:17], v[102:103]
	v_add_co_u32_e32 v102, vcc, s14, v110
	s_nop 1
	v_addc_co_u32_e32 v103, vcc, 0, v111, vcc
	v_add_co_u32_e32 v104, vcc, s15, v110
	s_nop 1
	v_addc_co_u32_e32 v105, vcc, 0, v111, vcc
	global_store_dwordx4 v[104:105], v[98:101], off offset:-4096
	s_nop 1
	v_lshlrev_b32_e32 v98, 16, v96
	v_and_b32_e32 v99, 0xffff0000, v96
	v_lshlrev_b32_e32 v96, 16, v97
	v_and_b32_e32 v97, 0xffff0000, v97
	v_pk_mul_f32 v[100:101], v[64:65], v[98:99] op_sel_hi:[0,1]
	v_pk_mul_f32 v[96:97], v[64:65], v[96:97] op_sel_hi:[0,1]
	v_pk_mul_f32 v[98:99], v[22:23], v[96:97]
	v_pk_mul_f32 v[96:97], v[20:21], v[100:101]
	global_store_dwordx4 v[102:103], v[96:99], off offset:1024
	s_nop 1
	v_lshlrev_b32_e32 v96, 16, v94
	v_and_b32_e32 v97, 0xffff0000, v94
	v_lshlrev_b32_e32 v94, 16, v95
	v_and_b32_e32 v95, 0xffff0000, v95
	v_pk_mul_f32 v[98:99], v[64:65], v[96:97] op_sel_hi:[0,1]
	v_pk_mul_f32 v[94:95], v[64:65], v[94:95] op_sel_hi:[0,1]
	v_pk_mul_f32 v[96:97], v[26:27], v[94:95]
	v_pk_mul_f32 v[94:95], v[24:25], v[98:99]
	global_store_dwordx4 v[102:103], v[94:97], off offset:2048
	s_nop 1
	v_lshlrev_b32_e32 v94, 16, v90
	v_and_b32_e32 v95, 0xffff0000, v90
	v_lshlrev_b32_e32 v90, 16, v91
	v_and_b32_e32 v91, 0xffff0000, v91
	v_pk_mul_f32 v[94:95], v[64:65], v[94:95] op_sel_hi:[0,1]
	v_pk_mul_f32 v[90:91], v[64:65], v[90:91] op_sel_hi:[0,1]
	v_pk_mul_f32 v[96:97], v[30:31], v[90:91]
	v_pk_mul_f32 v[94:95], v[28:29], v[94:95]
	s_waitcnt vmcnt(30)
	v_lshlrev_b32_e32 v90, 16, v88
	v_and_b32_e32 v91, 0xffff0000, v88
	v_lshlrev_b32_e32 v88, 16, v89
	v_and_b32_e32 v89, 0xffff0000, v89
	global_store_dwordx4 v[102:103], v[94:97], off offset:3072
	v_pk_mul_f32 v[88:89], v[64:65], v[88:89] op_sel_hi:[0,1]
	s_nop 0
	v_pk_mul_f32 v[94:95], v[64:65], v[90:91] op_sel_hi:[0,1]
	v_pk_mul_f32 v[90:91], v[34:35], v[88:89]
	v_pk_mul_f32 v[88:89], v[32:33], v[94:95]
	global_store_dwordx4 v[104:105], v[88:91], off
	s_waitcnt vmcnt(31)
	s_nop 0
	v_lshlrev_b32_e32 v88, 16, v86
	v_and_b32_e32 v89, 0xffff0000, v86
	v_lshlrev_b32_e32 v86, 16, v87
	v_and_b32_e32 v87, 0xffff0000, v87
	v_pk_mul_f32 v[90:91], v[64:65], v[88:89] op_sel_hi:[0,1]
	v_pk_mul_f32 v[86:87], v[64:65], v[86:87] op_sel_hi:[0,1]
	v_pk_mul_f32 v[88:89], v[38:39], v[86:87]
	v_pk_mul_f32 v[86:87], v[36:37], v[90:91]
	global_store_dwordx4 v[104:105], v[86:89], off offset:1024
	s_waitcnt vmcnt(31)
	s_nop 0
	v_lshlrev_b32_e32 v86, 16, v84
	v_and_b32_e32 v87, 0xffff0000, v84
	v_lshlrev_b32_e32 v84, 16, v85
	v_and_b32_e32 v85, 0xffff0000, v85
	v_pk_mul_f32 v[88:89], v[64:65], v[86:87] op_sel_hi:[0,1]
	v_pk_mul_f32 v[84:85], v[64:65], v[84:85] op_sel_hi:[0,1]
	v_pk_mul_f32 v[86:87], v[42:43], v[84:85]
	v_pk_mul_f32 v[84:85], v[40:41], v[88:89]
	global_store_dwordx4 v[104:105], v[84:87], off offset:2048
	s_waitcnt vmcnt(31)
	s_nop 0
	v_lshlrev_b32_e32 v84, 16, v82
	v_and_b32_e32 v85, 0xffff0000, v82
	v_lshlrev_b32_e32 v82, 16, v83
	v_and_b32_e32 v83, 0xffff0000, v83
	v_pk_mul_f32 v[86:87], v[64:65], v[84:85] op_sel_hi:[0,1]
	v_pk_mul_f32 v[82:83], v[64:65], v[82:83] op_sel_hi:[0,1]
	v_pk_mul_f32 v[84:85], v[46:47], v[82:83]
	v_pk_mul_f32 v[82:83], v[44:45], v[86:87]
	global_store_dwordx4 v[104:105], v[82:85], off offset:3072
	s_waitcnt vmcnt(31)
	s_nop 0
	v_lshlrev_b32_e32 v82, 16, v80
	v_and_b32_e32 v83, 0xffff0000, v80
	v_lshlrev_b32_e32 v80, 16, v81
	v_and_b32_e32 v81, 0xffff0000, v81
	v_pk_mul_f32 v[84:85], v[64:65], v[82:83] op_sel_hi:[0,1]
	v_pk_mul_f32 v[80:81], v[64:65], v[80:81] op_sel_hi:[0,1]
	v_pk_mul_f32 v[82:83], v[50:51], v[80:81]
	v_pk_mul_f32 v[80:81], v[48:49], v[84:85]
	v_add_co_u32_e32 v84, vcc, s16, v110
	s_nop 1
	v_addc_co_u32_e32 v85, vcc, 0, v111, vcc
	global_store_dwordx4 v[84:85], v[80:83], off
	s_waitcnt vmcnt(31)
	s_nop 0
	v_lshlrev_b32_e32 v80, 16, v78
	v_and_b32_e32 v81, 0xffff0000, v78
	v_lshlrev_b32_e32 v78, 16, v79
	v_and_b32_e32 v79, 0xffff0000, v79
	v_pk_mul_f32 v[82:83], v[64:65], v[80:81] op_sel_hi:[0,1]
	v_pk_mul_f32 v[78:79], v[64:65], v[78:79] op_sel_hi:[0,1]
	v_pk_mul_f32 v[80:81], v[54:55], v[78:79]
	v_pk_mul_f32 v[78:79], v[52:53], v[82:83]
	global_store_dwordx4 v[84:85], v[78:81], off offset:1024
	s_waitcnt vmcnt(31)
	s_nop 0
	v_lshlrev_b32_e32 v78, 16, v76
	v_and_b32_e32 v79, 0xffff0000, v76
	v_lshlrev_b32_e32 v76, 16, v77
	v_and_b32_e32 v77, 0xffff0000, v77
	v_pk_mul_f32 v[80:81], v[64:65], v[78:79] op_sel_hi:[0,1]
	v_pk_mul_f32 v[76:77], v[64:65], v[76:77] op_sel_hi:[0,1]
	v_pk_mul_f32 v[78:79], v[58:59], v[76:77]
	v_pk_mul_f32 v[76:77], v[56:57], v[80:81]
	global_store_dwordx4 v[84:85], v[76:79], off offset:2048
	s_waitcnt vmcnt(31)
	s_nop 0
	v_lshlrev_b32_e32 v76, 16, v74
	v_and_b32_e32 v77, 0xffff0000, v74
	v_lshlrev_b32_e32 v74, 16, v75
	v_and_b32_e32 v75, 0xffff0000, v75
	v_pk_mul_f32 v[78:79], v[64:65], v[76:77] op_sel_hi:[0,1]
	v_pk_mul_f32 v[74:75], v[64:65], v[74:75] op_sel_hi:[0,1]
	v_pk_mul_f32 v[76:77], v[62:63], v[74:75]
	v_pk_mul_f32 v[74:75], v[60:61], v[78:79]
	global_store_dwordx4 v[84:85], v[74:77], off offset:3072
	s_branch .LBB0_1425
